# ConvGate epilogue: act stores of the two channel sub-blocks (n=0,1) merged into one 16-byte store per lane (dwordx4), halving store instructions and write fragments
# speedup vs baseline: 1.0200x; 1.0200x over previous
.LBB0_113:
	s_or_b64 exec, exec, s[0:1]
	v_ffbh_u32_e32 v0, v135
	v_min_u32_e32 v0, 32, v0
	v_lshlrev_b64 v[114:115], v0, v[134:135]
	v_min_u32_e32 v114, 1, v114
	v_or_b32_e32 v114, v115, v114
	v_cvt_f32_u32_e32 v114, v114
	v_sub_u32_e32 v0, 32, v0
	s_lshl_b32 s5, s78, 7
	v_add_u32_e32 v180, s5, v130
	v_ldexp_f32 v0, v114, v0
	v_fmamk_f32 v0, v0, 0x2e800000, v210
	s_nop 0
	v_rsq_f32_e32 v0, v0
	s_nop 0
	s_nop 0
	v_mov_b32_e32 v178, v0
	v_ffbh_u32_e32 v0, v133
	v_min_u32_e32 v0, 32, v0
	v_pk_mul_f32 v[186:187], v[110:111], v[178:179] op_sel_hi:[1,0]
	v_lshlrev_b64 v[110:111], v0, v[132:133]
	v_min_u32_e32 v110, 1, v110
	v_or_b32_e32 v110, v111, v110
	v_cvt_f32_u32_e32 v110, v110
	v_sub_u32_e32 v0, 32, v0
	v_pk_mul_f32 v[184:185], v[112:113], v[178:179] op_sel_hi:[1,0]
	v_ldexp_f32 v0, v110, v0
	v_fmamk_f32 v0, v0, 0x2e800000, v210
	s_nop 0
	v_rsq_f32_e32 v0, v0
	s_nop 0
	s_nop 0
	v_mov_b32_e32 v182, v0
	v_pk_mul_f32 v[188:189], v[108:109], v[182:183] op_sel_hi:[1,0]
	v_pk_mul_f32 v[198:199], v[106:107], v[182:183] op_sel_hi:[1,0]
	v_ashrrev_i32_e32 v181, 31, v180
	v_lshlrev_b64 v[118:119], 2, v[180:181]
	v_lshl_add_u64 v[106:107], s[44:45], 0, v[118:119]
	v_lshl_add_u64 v[108:109], s[60:61], 0, v[118:119]
	global_load_dwordx4 v[122:125], v[106:107], off
	global_load_dwordx4 v[126:129], v[108:109], off
	v_lshl_add_u64 v[106:107], s[2:3], 0, v[118:119]
	global_load_dwordx4 v[130:133], v[106:107], off
	v_lshl_add_u64 v[106:107], s[48:49], 0, v[118:119]
	global_load_dwordx4 v[134:137], v[106:107], off
	s_nop 1
	v_cmp_lt_u32_e32 vcc, 1, v183
	v_mov_b32_dpp v206, v170 row_ror:1 row_mask:0xf bank_mask:0xf
	v_mov_b32_dpp v204, v170 row_ror:2 row_mask:0xf bank_mask:0xf
	v_mov_b32_dpp v207, v171 row_ror:1 row_mask:0xf bank_mask:0xf
	v_mov_b32_dpp v205, v171 row_ror:2 row_mask:0xf bank_mask:0xf
	v_mov_b32_dpp v202, v172 row_ror:1 row_mask:0xf bank_mask:0xf
	v_mov_b32_dpp v200, v172 row_ror:2 row_mask:0xf bank_mask:0xf
	v_mov_b32_dpp v203, v173 row_ror:1 row_mask:0xf bank_mask:0xf
	v_mov_b32_dpp v201, v173 row_ror:2 row_mask:0xf bank_mask:0xf
	v_mov_b32_dpp v241, v186 row_ror:1 row_mask:0xf bank_mask:0xf
	v_mov_b32_dpp v240, v186 row_ror:2 row_mask:0xf bank_mask:0xf
	v_mov_b32_dpp v245, v187 row_ror:1 row_mask:0xf bank_mask:0xf
	v_mov_b32_dpp v244, v187 row_ror:2 row_mask:0xf bank_mask:0xf
	v_mov_b32_dpp v229, v184 row_ror:1 row_mask:0xf bank_mask:0xf
	v_mov_b32_dpp v228, v184 row_ror:2 row_mask:0xf bank_mask:0xf
	v_mov_b32_dpp v235, v185 row_ror:1 row_mask:0xf bank_mask:0xf
	v_mov_b32_dpp v233, v185 row_ror:2 row_mask:0xf bank_mask:0xf
	v_mov_b32_dpp v234, v198 row_ror:1 row_mask:0xf bank_mask:0xf
	v_mov_b32_dpp v231, v198 row_ror:2 row_mask:0xf bank_mask:0xf
	v_mov_b32_dpp v239, v199 row_ror:1 row_mask:0xf bank_mask:0xf
	v_mov_b32_dpp v237, v199 row_ror:2 row_mask:0xf bank_mask:0xf
	v_mov_b32_dpp v151, v188 row_ror:1 row_mask:0xf bank_mask:0xf
	v_mov_b32_dpp v0, v188 row_ror:2 row_mask:0xf bank_mask:0xf
	v_mov_b32_dpp v227, v189 row_ror:1 row_mask:0xf bank_mask:0xf
	v_mov_b32_dpp v213, v189 row_ror:2 row_mask:0xf bank_mask:0xf
	v_mov_b32_dpp v243, v176 row_ror:1 row_mask:0xf bank_mask:0xf
	v_mov_b32_dpp v242, v176 row_ror:2 row_mask:0xf bank_mask:0xf
	v_mov_b32_dpp v247, v177 row_ror:1 row_mask:0xf bank_mask:0xf
	v_mov_b32_dpp v246, v177 row_ror:2 row_mask:0xf bank_mask:0xf
	v_mov_b32_dpp v232, v174 row_ror:1 row_mask:0xf bank_mask:0xf
	v_mov_b32_dpp v230, v174 row_ror:2 row_mask:0xf bank_mask:0xf
	v_mov_b32_dpp v238, v175 row_ror:1 row_mask:0xf bank_mask:0xf
	v_mov_b32_dpp v236, v175 row_ror:2 row_mask:0xf bank_mask:0xf
	v_lshl_add_u64 v[106:107], s[96:97], 0, v[118:119]
	v_lshl_add_u64 v[108:109], s[62:63], 0, v[118:119]
	global_load_dwordx4 v[114:117], v[106:107], off
	global_load_dwordx4 v[110:113], v[108:109], off
	v_lshl_add_u64 v[106:107], s[64:65], 0, v[118:119]
	v_lshl_add_u64 v[118:119], s[66:67], 0, v[118:119]
	global_load_dwordx4 v[106:109], v[106:107], off
	s_nop 1
	global_load_dwordx4 v[118:121], v[118:119], off
	s_nop 1
	v_mov_b32_dpp v190, v158 row_ror:1 row_mask:0xf bank_mask:0xf
	v_mov_b32_dpp v194, v158 row_ror:2 row_mask:0xf bank_mask:0xf
	v_mov_b32_dpp v191, v159 row_ror:1 row_mask:0xf bank_mask:0xf
	v_mov_b32_dpp v195, v159 row_ror:2 row_mask:0xf bank_mask:0xf
	v_mov_b32_dpp v192, v156 row_ror:1 row_mask:0xf bank_mask:0xf
	v_mov_b32_dpp v196, v156 row_ror:2 row_mask:0xf bank_mask:0xf
	v_mov_b32_dpp v193, v157 row_ror:1 row_mask:0xf bank_mask:0xf
	v_mov_b32_dpp v197, v157 row_ror:2 row_mask:0xf bank_mask:0xf
	s_and_saveexec_b64 s[0:1], vcc
	s_mov_b32 s50, 0x20000
	s_mov_b32 s47, 0xbfb8aa3b
	s_cbranch_execz .Lcg_skip0
	s_waitcnt vmcnt(4)
	v_pk_fma_f32 v[248:249], v[124:125], v[200:201], v[136:137]
	s_nop 0
	v_pk_fma_f32 v[248:249], v[128:129], v[202:203], v[248:249]
	s_nop 0
	v_pk_fma_f32 v[172:173], v[172:173], v[132:133], v[248:249]
	v_pk_fma_f32 v[248:249], v[122:123], v[204:205], v[134:135]
	v_pk_fma_f32 v[248:249], v[126:127], v[206:207], v[248:249]
	v_pk_fma_f32 v[170:171], v[170:171], v[130:131], v[248:249]
	v_pk_mul_f32 v[248:249], v[170:171], s[98:99] op_sel_hi:[1,0]
	v_pk_mul_f32 v[250:251], v[172:173], s[98:99] op_sel_hi:[1,0]
	v_exp_f32_e32 v248, v248
	v_exp_f32_e32 v249, v249
	v_exp_f32_e32 v250, v250
	v_exp_f32_e32 v251, v251
	v_pk_add_f32 v[248:249], v[248:249], 1.0 op_sel_hi:[1,0]
	v_pk_add_f32 v[250:251], v[250:251], 1.0 op_sel_hi:[1,0]
	v_rcp_f32_e32 v248, v248
	v_rcp_f32_e32 v249, v249
	v_rcp_f32_e32 v250, v250
	v_rcp_f32_e32 v251, v251
	v_pk_mul_f32 v[170:171], v[170:171], v[248:249]
	v_pk_mul_f32 v[172:173], v[172:173], v[250:251]
	s_waitcnt vmcnt(0)
	v_pk_fma_f32 v[248:249], v[116:117], v[196:197], v[120:121]
	v_pk_fma_f32 v[250:251], v[114:115], v[194:195], v[118:119]
	v_pk_fma_f32 v[248:249], v[112:113], v[192:193], v[248:249]
	v_pk_fma_f32 v[250:251], v[110:111], v[190:191], v[250:251]
	v_pk_fma_f32 v[156:157], v[156:157], v[108:109], v[248:249]
	v_pk_fma_f32 v[158:159], v[158:159], v[106:107], v[250:251]
	v_pk_mul_f32 v[156:157], v[172:173], v[156:157]
	v_pk_mul_f32 v[158:159], v[170:171], v[158:159]
	s_nop 0
	v_cvt_pk_bf16_f32 v158, v158, v159
	v_cvt_pk_bf16_f32 v159, v156, v157
	v_mov_b64_e32 v[156:157], s[36:37]
	v_mad_i64_i32 v[156:157], s[28:29], v150, s46, v[156:157]
	v_lshl_add_u64 v[156:157], v[180:181], 1, v[156:157]
	v_mov_b32_e32 v248, v158
	v_mov_b32_e32 v249, v159
.LBB0_115:
	s_or_b64 exec, exec, s[0:1]
	v_cmp_eq_u32_e64 s[42:43], 0, v183
	v_cndmask_b32_e32 v159, v205, v244, vcc
	v_cndmask_b32_e32 v158, v204, v240, vcc
	v_cndmask_b32_e64 v157, v245, v207, s[42:43]
	v_cndmask_b32_e64 v156, v241, v206, s[42:43]
	s_waitcnt vmcnt(4)
	v_pk_fma_f32 v[158:159], v[122:123], v[158:159], v[134:135]
	v_cndmask_b32_e32 v173, v201, v233, vcc
	v_cndmask_b32_e32 v172, v200, v228, vcc
	v_pk_fma_f32 v[156:157], v[126:127], v[156:157], v[158:159]
	v_cndmask_b32_e64 v171, v235, v203, s[42:43]
	v_cndmask_b32_e64 v170, v229, v202, s[42:43]
	v_pk_fma_f32 v[172:173], v[124:125], v[172:173], v[136:137]
	v_pk_fma_f32 v[156:157], v[186:187], v[130:131], v[156:157]
	v_pk_fma_f32 v[170:171], v[128:129], v[170:171], v[172:173]
	v_cndmask_b32_e32 v187, v244, v237, vcc
	v_cndmask_b32_e32 v186, v240, v231, vcc
	v_pk_fma_f32 v[170:171], v[184:185], v[132:133], v[170:171]
	v_cndmask_b32_e64 v185, v239, v245, s[42:43]
	v_cndmask_b32_e64 v184, v234, v241, s[42:43]
	v_pk_fma_f32 v[186:187], v[122:123], v[186:187], v[134:135]
	v_cndmask_b32_e32 v201, v233, v213, vcc
	v_pk_fma_f32 v[184:185], v[126:127], v[184:185], v[186:187]
	v_cndmask_b32_e32 v200, v228, v0, vcc
	v_pk_fma_f32 v[184:185], v[198:199], v[130:131], v[184:185]
	v_cndmask_b32_e64 v199, v227, v235, s[42:43]
	v_cndmask_b32_e64 v198, v151, v229, s[42:43]
	v_pk_fma_f32 v[200:201], v[124:125], v[200:201], v[136:137]
	v_cndmask_b32_e32 v203, v237, v246, vcc
	v_cndmask_b32_e32 v202, v231, v242, vcc
	v_pk_fma_f32 v[198:199], v[128:129], v[198:199], v[200:201]
	v_cndmask_b32_e64 v201, v247, v239, s[42:43]
	v_cndmask_b32_e64 v200, v243, v234, s[42:43]
	v_pk_fma_f32 v[122:123], v[122:123], v[202:203], v[134:135]
	v_cndmask_b32_e32 v135, v213, v236, vcc
	v_pk_fma_f32 v[122:123], v[126:127], v[200:201], v[122:123]
	v_cndmask_b32_e32 v134, v0, v230, vcc
	v_pk_fma_f32 v[122:123], v[176:177], v[130:131], v[122:123]
	v_cndmask_b32_e64 v131, v238, v227, s[42:43]
	v_cndmask_b32_e64 v130, v232, v151, s[42:43]
	v_pk_fma_f32 v[124:125], v[124:125], v[134:135], v[136:137]
	v_pk_fma_f32 v[124:125], v[128:129], v[130:131], v[124:125]
	v_mov_b32_e32 v179, v178
	v_pk_fma_f32 v[124:125], v[174:175], v[132:133], v[124:125]
	v_mov_b32_e32 v183, v182
	v_mov_b32_e32 v130, v178
	v_mov_b32_e32 v131, v178
	v_pk_mul_f32 v[104:105], v[104:105], v[130:131]
	v_pk_mul_f32 v[102:103], v[102:103], v[178:179]
	v_pk_mul_f32 v[98:99], v[98:99], v[182:183]
	s_nop 1
	v_mov_b32_e32 v130, v182
	v_mov_b32_e32 v131, v182
	s_nop 1
	v_mov_b32_dpp v177, v102 row_ror:2 row_mask:0xf bank_mask:0xf
	s_nop 1
	v_mov_b32_dpp v179, v103 row_ror:2 row_mask:0xf bank_mask:0xf
	s_nop 1
	v_mov_b32_dpp v183, v104 row_ror:2 row_mask:0xf bank_mask:0xf
	s_nop 1
	v_mov_b32_dpp v201, v105 row_ror:2 row_mask:0xf bank_mask:0xf
	v_pk_fma_f32 v[188:189], v[188:189], v[132:133], v[198:199]
	v_pk_mul_f32 v[100:101], v[100:101], v[130:131]
	v_mov_b32_dpp v176, v102 row_ror:1 row_mask:0xf bank_mask:0xf
	v_mov_b32_dpp v178, v103 row_ror:1 row_mask:0xf bank_mask:0xf
	v_mov_b32_dpp v182, v104 row_ror:1 row_mask:0xf bank_mask:0xf
	v_mov_b32_dpp v200, v105 row_ror:1 row_mask:0xf bank_mask:0xf
	v_cndmask_b32_e32 v130, v194, v177, vcc
	v_cndmask_b32_e32 v131, v195, v179, vcc
	v_cndmask_b32_e32 v132, v196, v183, vcc
	v_cndmask_b32_e32 v133, v197, v201, vcc
	v_cndmask_b32_e64 v134, v176, v190, s[42:43]
	v_cndmask_b32_e64 v135, v178, v191, s[42:43]
	v_cndmask_b32_e64 v136, v182, v192, s[42:43]
	v_cndmask_b32_e64 v137, v200, v193, s[42:43]
	s_waitcnt vmcnt(1)
	v_pk_fma_f32 v[132:133], v[116:117], v[132:133], v[120:121]
	v_pk_fma_f32 v[130:131], v[114:115], v[130:131], v[118:119]
	v_pk_fma_f32 v[132:133], v[112:113], v[136:137], v[132:133]
	v_pk_fma_f32 v[130:131], v[110:111], v[134:135], v[130:131]
	v_or_b32_e32 v0, 16, v150
	v_or_b32_e32 v174, 32, v150
	v_or_b32_e32 v175, 48, v150
	v_pk_mul_f32 v[158:159], v[156:157], s[98:99] op_sel_hi:[1,0]
	v_pk_mul_f32 v[172:173], v[170:171], s[98:99] op_sel_hi:[1,0]
	v_exp_f32_e32 v158, v158
	v_exp_f32_e32 v159, v159
	v_exp_f32_e32 v172, v172
	v_exp_f32_e32 v173, v173
	v_pk_add_f32 v[158:159], v[158:159], 1.0 op_sel_hi:[1,0]
	v_pk_add_f32 v[172:173], v[172:173], 1.0 op_sel_hi:[1,0]
	v_rcp_f32_e32 v158, v158
	v_rcp_f32_e32 v159, v159
	v_rcp_f32_e32 v172, v172
	v_rcp_f32_e32 v173, v173
	v_pk_mul_f32 v[150:151], v[156:157], v[158:159]
	v_pk_mul_f32 v[156:157], v[170:171], v[172:173]
	v_pk_fma_f32 v[104:105], v[104:105], v[108:109], v[132:133]
	v_pk_fma_f32 v[102:103], v[102:103], v[106:107], v[130:131]
	v_pk_mul_f32 v[104:105], v[156:157], v[104:105]
	v_pk_mul_f32 v[102:103], v[150:151], v[102:103]
	v_cvt_pk_bf16_f32 v102, v102, v103
	v_cvt_pk_bf16_f32 v103, v104, v105
	v_mov_b64_e32 v[104:105], s[36:37]
	v_mad_i64_i32 v[130:131], s[0:1], v0, s46, v[104:105]
	v_lshlrev_b64 v[132:133], 1, v[180:181]
	s_nop 1
	v_lshl_add_u64 v[130:131], v[130:131], 0, v[132:133]
	s_nop 1
	v_mov_b32_dpp v158, v98 row_ror:2 row_mask:0xf bank_mask:0xf
	s_nop 1
	v_mov_b32_dpp v170, v99 row_ror:2 row_mask:0xf bank_mask:0xf
	s_nop 1
	v_mov_b32_dpp v172, v100 row_ror:2 row_mask:0xf bank_mask:0xf
	s_nop 1
	v_mov_b32_dpp v180, v101 row_ror:2 row_mask:0xf bank_mask:0xf
	v_mov_b32_e32 v250, v102
	v_mov_b32_e32 v251, v103
	v_mov_b32_dpp v0, v98 row_ror:1 row_mask:0xf bank_mask:0xf
	v_mov_b32_dpp v159, v99 row_ror:1 row_mask:0xf bank_mask:0xf
	v_mov_b32_dpp v171, v100 row_ror:1 row_mask:0xf bank_mask:0xf
	v_mov_b32_dpp v173, v101 row_ror:1 row_mask:0xf bank_mask:0xf
	v_cndmask_b32_e32 v102, v177, v158, vcc
	v_cndmask_b32_e32 v103, v179, v170, vcc
	v_cndmask_b32_e32 v130, v183, v172, vcc
	v_cndmask_b32_e32 v131, v201, v180, vcc
	v_cndmask_b32_e64 v134, v0, v176, s[42:43]
	v_cndmask_b32_e64 v135, v159, v178, s[42:43]
	v_cndmask_b32_e64 v136, v171, v182, s[42:43]
	v_cndmask_b32_e64 v137, v173, v200, s[42:43]
	v_pk_fma_f32 v[130:131], v[116:117], v[130:131], v[120:121]
	v_pk_fma_f32 v[102:103], v[114:115], v[102:103], v[118:119]
	v_pk_fma_f32 v[130:131], v[112:113], v[136:137], v[130:131]
	v_pk_fma_f32 v[102:103], v[110:111], v[134:135], v[102:103]
	v_pk_mul_f32 v[186:187], v[184:185], s[98:99] op_sel_hi:[1,0]
	v_pk_mul_f32 v[198:199], v[188:189], s[98:99] op_sel_hi:[1,0]
	v_exp_f32_e32 v186, v186
	v_exp_f32_e32 v187, v187
	v_exp_f32_e32 v198, v198
	v_exp_f32_e32 v199, v199
	v_pk_add_f32 v[186:187], v[186:187], 1.0 op_sel_hi:[1,0]
	v_pk_add_f32 v[198:199], v[198:199], 1.0 op_sel_hi:[1,0]
	v_rcp_f32_e32 v186, v186
	v_rcp_f32_e32 v187, v187
	v_rcp_f32_e32 v198, v198
	v_rcp_f32_e32 v199, v199
	v_pk_mul_f32 v[150:151], v[184:185], v[186:187]
	v_pk_mul_f32 v[156:157], v[188:189], v[198:199]
	v_pk_fma_f32 v[100:101], v[100:101], v[108:109], v[130:131]
	v_pk_fma_f32 v[98:99], v[98:99], v[106:107], v[102:103]
	v_pk_mul_f32 v[100:101], v[156:157], v[100:101]
	v_pk_mul_f32 v[98:99], v[150:151], v[98:99]
	v_cvt_pk_bf16_f32 v98, v98, v99
	v_cvt_pk_bf16_f32 v99, v100, v101
	v_mad_i64_i32 v[100:101], s[0:1], v174, s46, v[104:105]
	v_lshl_add_u64 v[100:101], v[100:101], 0, v[132:133]
	v_mov_b32_e32 v244, v98
	v_mov_b32_e32 v245, v99
	s_nop 1
	s_nop 1
	v_mov_b32_dpp v98, v154 row_ror:2 row_mask:0xf bank_mask:0xf
	s_nop 1
	v_mov_b32_dpp v99, v155 row_ror:2 row_mask:0xf bank_mask:0xf
	s_nop 1
	v_mov_b32_dpp v100, v152 row_ror:2 row_mask:0xf bank_mask:0xf
	s_nop 1
	v_mov_b32_dpp v101, v153 row_ror:2 row_mask:0xf bank_mask:0xf
	v_mov_b32_dpp v102, v154 row_ror:1 row_mask:0xf bank_mask:0xf
	v_mov_b32_dpp v103, v155 row_ror:1 row_mask:0xf bank_mask:0xf
	v_mov_b32_dpp v130, v152 row_ror:1 row_mask:0xf bank_mask:0xf
	v_mov_b32_dpp v131, v153 row_ror:1 row_mask:0xf bank_mask:0xf
	v_cndmask_b32_e32 v98, v158, v98, vcc
	v_cndmask_b32_e32 v99, v170, v99, vcc
	v_cndmask_b32_e32 v100, v172, v100, vcc
	v_cndmask_b32_e32 v101, v180, v101, vcc
	v_cndmask_b32_e64 v102, v102, v0, s[42:43]
	v_cndmask_b32_e64 v103, v103, v159, s[42:43]
	v_cndmask_b32_e64 v130, v130, v171, s[42:43]
	v_cndmask_b32_e64 v131, v131, v173, s[42:43]
	v_pk_fma_f32 v[98:99], v[114:115], v[98:99], v[118:119]
	v_pk_fma_f32 v[100:101], v[116:117], v[100:101], v[120:121]
	v_pk_fma_f32 v[98:99], v[110:111], v[102:103], v[98:99]
	v_pk_fma_f32 v[100:101], v[112:113], v[130:131], v[100:101]
	v_pk_mul_f32 v[126:127], v[122:123], s[98:99] op_sel_hi:[1,0]
	v_pk_mul_f32 v[128:129], v[124:125], s[98:99] op_sel_hi:[1,0]
	v_exp_f32_e32 v126, v126
	v_exp_f32_e32 v127, v127
	v_exp_f32_e32 v128, v128
	v_exp_f32_e32 v129, v129
	v_pk_add_f32 v[126:127], v[126:127], 1.0 op_sel_hi:[1,0]
	v_pk_add_f32 v[128:129], v[128:129], 1.0 op_sel_hi:[1,0]
	v_rcp_f32_e32 v126, v126
	v_rcp_f32_e32 v127, v127
	v_rcp_f32_e32 v128, v128
	v_rcp_f32_e32 v129, v129
	v_pk_mul_f32 v[122:123], v[122:123], v[126:127]
	v_pk_mul_f32 v[124:125], v[124:125], v[128:129]
	v_pk_fma_f32 v[98:99], v[154:155], v[106:107], v[98:99]
	v_pk_fma_f32 v[100:101], v[152:153], v[108:109], v[100:101]
	v_pk_mul_f32 v[98:99], v[122:123], v[98:99]
	v_pk_mul_f32 v[100:101], v[124:125], v[100:101]
	v_cvt_pk_bf16_f32 v98, v98, v99
	s_nop 0
	v_cvt_pk_bf16_f32 v99, v100, v101
	v_mad_i64_i32 v[100:101], s[0:1], v175, s46, v[104:105]
	v_lshl_add_u64 v[100:101], v[100:101], 0, v[132:133]
	v_mov_b32_e32 v246, v98
	v_mov_b32_e32 v247, v99
	s_add_i32 s0, s6, 2
	v_and_b32_e32 v129, 15, v226
	v_or_b32_e32 v106, s4, v129
	v_ashrrev_i32_e32 v107, 31, v106
	v_lshl_add_u64 v[104:105], v[106:107], 3, s[38:39]
	global_load_dwordx2 v[108:109], v[104:105], off offset:1024
	global_load_dwordx2 v[102:103], v[104:105], off offset:1152
	global_load_dwordx2 v[100:101], v[104:105], off offset:1280
	s_nop 0
	global_load_dwordx2 v[104:105], v[104:105], off offset:1408
	v_ashrrev_i32_e32 v0, 1, v226
	v_and_b32_e32 v0, -8, v0
	v_add_u32_e32 v98, s21, v0
	s_mul_hi_i32 s1, s0, 0xb000
	s_mul_i32 s0, s0, 0xb000
	s_add_u32 s0, s18, s0
	s_addc_u32 s1, s19, s1
	s_add_u32 s78, s0, s80
	s_addc_u32 s79, s1, s81
	s_waitcnt vmcnt(3)
	v_ffbh_u32_e32 v0, v109
	v_min_u32_e32 v0, 32, v0
	v_lshlrev_b64 v[108:109], v0, v[108:109]
	v_min_u32_e32 v99, 1, v108
	v_or_b32_e32 v99, v109, v99
	v_cvt_f32_u32_e32 v99, v99
	v_sub_u32_e32 v0, 32, v0
	v_ldexp_f32 v0, v99, v0
	v_fmamk_f32 v0, v0, 0x2e800000, v210
	s_nop 0
	v_rsq_f32_e32 v0, v0
	s_nop 0
	s_nop 0
	v_ashrrev_i32_e32 v99, 31, v98
	v_pk_mul_f32 v[118:119], v[96:97], v[0:1] op_sel_hi:[1,0]
	v_pk_mul_f32 v[116:117], v[94:95], v[0:1] op_sel_hi:[1,0]
	v_pk_mul_f32 v[112:113], v[92:93], v[0:1] op_sel_hi:[1,0]
	v_pk_mul_f32 v[114:115], v[90:91], v[0:1] op_sel_hi:[1,0]
	v_lshl_add_u64 v[90:91], v[98:99], 1, s[78:79]
	v_cmp_gt_u32_e32 vcc, 2, v129
	s_and_saveexec_b64 s[0:1], vcc
	s_cbranch_execz .LBB0_117
	v_mul_u32_u24_e32 v0, 0x1600, v129
	v_lshlrev_b32_e32 v0, 1, v0
	v_cvt_pk_bf16_f32 v92, v116, v117
	v_cvt_pk_bf16_f32 v93, v118, v119
	v_lshl_add_u64 v[96:97], v[90:91], 0, v[0:1]
	v_cvt_pk_bf16_f32 v94, v114, v115
	v_cvt_pk_bf16_f32 v95, v112, v113
	global_store_dwordx2 v[96:97], v[92:93], off
	global_store_dwordx2 v[96:97], v[94:95], off offset:256

.LBB0_119:
	s_or_b64 exec, exec, s[0:1]
	v_ffbh_u32_e32 v0, v103
	v_min_u32_e32 v0, 32, v0
	v_lshlrev_b64 v[82:83], v0, v[102:103]
	v_min_u32_e32 v82, 1, v82
	v_or_b32_e32 v82, v83, v82
	v_cvt_f32_u32_e32 v82, v82
	v_sub_u32_e32 v0, 32, v0
	v_add_u32_e32 v126, s5, v98
	v_ldexp_f32 v0, v82, v0
	v_fmamk_f32 v0, v0, 0x2e800000, v210
	s_nop 0
	v_rsq_f32_e32 v0, v0
	s_nop 0
	s_nop 0
	v_mov_b32_e32 v124, v0
	v_ffbh_u32_e32 v0, v101
	v_min_u32_e32 v0, 32, v0
	v_pk_mul_f32 v[132:133], v[78:79], v[124:125] op_sel_hi:[1,0]
	v_lshlrev_b64 v[78:79], v0, v[100:101]
	v_min_u32_e32 v78, 1, v78
	v_or_b32_e32 v78, v79, v78
	v_cvt_f32_u32_e32 v78, v78
	v_sub_u32_e32 v0, 32, v0
	v_pk_mul_f32 v[130:131], v[80:81], v[124:125] op_sel_hi:[1,0]
	v_ldexp_f32 v0, v78, v0
	v_fmamk_f32 v0, v0, 0x2e800000, v210
	s_nop 0
	v_rsq_f32_e32 v0, v0
	s_nop 0
	s_nop 0
	v_mov_b32_e32 v128, v0
	v_pk_mul_f32 v[134:135], v[76:77], v[128:129] op_sel_hi:[1,0]
	v_pk_mul_f32 v[156:157], v[74:75], v[128:129] op_sel_hi:[1,0]
	v_ashrrev_i32_e32 v127, 31, v126
	v_lshlrev_b64 v[86:87], 2, v[126:127]
	v_lshl_add_u64 v[74:75], s[44:45], 0, v[86:87]
	v_lshl_add_u64 v[76:77], s[60:61], 0, v[86:87]
	global_load_dwordx4 v[90:93], v[74:75], off
	global_load_dwordx4 v[94:97], v[76:77], off
	v_lshl_add_u64 v[74:75], s[2:3], 0, v[86:87]
	global_load_dwordx4 v[98:101], v[74:75], off
	v_lshl_add_u64 v[74:75], s[48:49], 0, v[86:87]
	global_load_dwordx4 v[102:105], v[74:75], off
	s_nop 1
	v_cmp_lt_u32_e32 vcc, 1, v129
	v_mov_b32_dpp v174, v116 row_ror:1 row_mask:0xf bank_mask:0xf
	v_mov_b32_dpp v172, v116 row_ror:2 row_mask:0xf bank_mask:0xf
	v_mov_b32_dpp v175, v117 row_ror:1 row_mask:0xf bank_mask:0xf
	v_mov_b32_dpp v173, v117 row_ror:2 row_mask:0xf bank_mask:0xf
	v_mov_b32_dpp v170, v118 row_ror:1 row_mask:0xf bank_mask:0xf
	v_mov_b32_dpp v158, v118 row_ror:2 row_mask:0xf bank_mask:0xf
	v_mov_b32_dpp v171, v119 row_ror:1 row_mask:0xf bank_mask:0xf
	v_mov_b32_dpp v159, v119 row_ror:2 row_mask:0xf bank_mask:0xf
	v_mov_b32_dpp v191, v132 row_ror:1 row_mask:0xf bank_mask:0xf
	v_mov_b32_dpp v190, v132 row_ror:2 row_mask:0xf bank_mask:0xf
	v_mov_b32_dpp v195, v133 row_ror:1 row_mask:0xf bank_mask:0xf
	v_mov_b32_dpp v194, v133 row_ror:2 row_mask:0xf bank_mask:0xf
	v_mov_b32_dpp v179, v130 row_ror:1 row_mask:0xf bank_mask:0xf
	v_mov_b32_dpp v178, v130 row_ror:2 row_mask:0xf bank_mask:0xf
	v_mov_b32_dpp v185, v131 row_ror:1 row_mask:0xf bank_mask:0xf
	v_mov_b32_dpp v183, v131 row_ror:2 row_mask:0xf bank_mask:0xf
	v_mov_b32_dpp v184, v156 row_ror:1 row_mask:0xf bank_mask:0xf
	v_mov_b32_dpp v181, v156 row_ror:2 row_mask:0xf bank_mask:0xf
	v_mov_b32_dpp v189, v157 row_ror:1 row_mask:0xf bank_mask:0xf
	v_mov_b32_dpp v187, v157 row_ror:2 row_mask:0xf bank_mask:0xf
	v_mov_b32_dpp v107, v134 row_ror:1 row_mask:0xf bank_mask:0xf
	v_mov_b32_dpp v0, v134 row_ror:2 row_mask:0xf bank_mask:0xf
	v_mov_b32_dpp v177, v135 row_ror:1 row_mask:0xf bank_mask:0xf
	v_mov_b32_dpp v176, v135 row_ror:2 row_mask:0xf bank_mask:0xf
	v_mov_b32_dpp v193, v122 row_ror:1 row_mask:0xf bank_mask:0xf
	v_mov_b32_dpp v192, v122 row_ror:2 row_mask:0xf bank_mask:0xf
	v_mov_b32_dpp v197, v123 row_ror:1 row_mask:0xf bank_mask:0xf
	v_mov_b32_dpp v196, v123 row_ror:2 row_mask:0xf bank_mask:0xf
	v_mov_b32_dpp v182, v120 row_ror:1 row_mask:0xf bank_mask:0xf
	v_mov_b32_dpp v180, v120 row_ror:2 row_mask:0xf bank_mask:0xf
	v_mov_b32_dpp v188, v121 row_ror:1 row_mask:0xf bank_mask:0xf
	v_mov_b32_dpp v186, v121 row_ror:2 row_mask:0xf bank_mask:0xf
	v_lshl_add_u64 v[74:75], s[96:97], 0, v[86:87]
	v_lshl_add_u64 v[76:77], s[62:63], 0, v[86:87]
	global_load_dwordx4 v[82:85], v[74:75], off
	global_load_dwordx4 v[78:81], v[76:77], off
	v_lshl_add_u64 v[74:75], s[64:65], 0, v[86:87]
	v_lshl_add_u64 v[86:87], s[66:67], 0, v[86:87]
	global_load_dwordx4 v[74:77], v[74:75], off
	s_nop 1
	global_load_dwordx4 v[86:89], v[86:87], off
	s_nop 1
	v_mov_b32_dpp v136, v114 row_ror:1 row_mask:0xf bank_mask:0xf
	v_mov_b32_dpp v152, v114 row_ror:2 row_mask:0xf bank_mask:0xf
	v_mov_b32_dpp v137, v115 row_ror:1 row_mask:0xf bank_mask:0xf
	v_mov_b32_dpp v153, v115 row_ror:2 row_mask:0xf bank_mask:0xf
	v_mov_b32_dpp v150, v112 row_ror:1 row_mask:0xf bank_mask:0xf
	v_mov_b32_dpp v154, v112 row_ror:2 row_mask:0xf bank_mask:0xf
	v_mov_b32_dpp v151, v113 row_ror:1 row_mask:0xf bank_mask:0xf
	v_mov_b32_dpp v155, v113 row_ror:2 row_mask:0xf bank_mask:0xf
	s_and_saveexec_b64 s[0:1], vcc
	s_cbranch_execz .Lcg_skip1
	s_waitcnt vmcnt(4)
	v_pk_fma_f32 v[198:199], v[92:93], v[158:159], v[104:105]
	s_nop 0
	v_pk_fma_f32 v[198:199], v[96:97], v[170:171], v[198:199]
	s_nop 0
	v_pk_fma_f32 v[118:119], v[118:119], v[100:101], v[198:199]
	v_pk_fma_f32 v[198:199], v[90:91], v[172:173], v[102:103]
	v_pk_fma_f32 v[198:199], v[94:95], v[174:175], v[198:199]
	v_pk_fma_f32 v[116:117], v[116:117], v[98:99], v[198:199]
	v_add_u32_e32 v125, 0x80, v106
	v_pk_mul_f32 v[198:199], v[116:117], s[98:99] op_sel_hi:[1,0]
	v_pk_mul_f32 v[200:201], v[118:119], s[98:99] op_sel_hi:[1,0]
	v_exp_f32_e32 v198, v198
	v_exp_f32_e32 v199, v199
	v_exp_f32_e32 v200, v200
	v_exp_f32_e32 v201, v201
	v_pk_add_f32 v[198:199], v[198:199], 1.0 op_sel_hi:[1,0]
	v_pk_add_f32 v[200:201], v[200:201], 1.0 op_sel_hi:[1,0]
	v_rcp_f32_e32 v198, v198
	v_rcp_f32_e32 v199, v199
	v_rcp_f32_e32 v200, v200
	v_rcp_f32_e32 v201, v201
	v_pk_mul_f32 v[116:117], v[116:117], v[198:199]
	v_pk_mul_f32 v[118:119], v[118:119], v[200:201]
	s_waitcnt vmcnt(0)
	v_pk_fma_f32 v[198:199], v[84:85], v[154:155], v[88:89]
	v_pk_fma_f32 v[200:201], v[82:83], v[152:153], v[86:87]
	v_pk_fma_f32 v[198:199], v[80:81], v[150:151], v[198:199]
	v_pk_fma_f32 v[200:201], v[78:79], v[136:137], v[200:201]
	v_pk_fma_f32 v[112:113], v[112:113], v[76:77], v[198:199]
	v_pk_fma_f32 v[114:115], v[114:115], v[74:75], v[200:201]
	v_pk_mul_f32 v[112:113], v[118:119], v[112:113]
	v_pk_mul_f32 v[114:115], v[116:117], v[114:115]
	s_nop 0
	v_cvt_pk_bf16_f32 v114, v114, v115
	v_cvt_pk_bf16_f32 v115, v112, v113
	v_mov_b64_e32 v[112:113], s[36:37]
	v_mad_i64_i32 v[112:113], s[6:7], v125, s46, v[112:113]
	v_lshl_add_u64 v[112:113], v[126:127], 1, v[112:113]
	v_mov_b32_e32 v228, v114
	v_mov_b32_e32 v229, v115
.LBB0_121:
	s_or_b64 exec, exec, s[0:1]
	v_cmp_eq_u32_e64 s[42:43], 0, v129
	v_cndmask_b32_e32 v115, v173, v194, vcc
	v_cndmask_b32_e32 v114, v172, v190, vcc
	v_cndmask_b32_e64 v113, v195, v175, s[42:43]
	v_cndmask_b32_e64 v112, v191, v174, s[42:43]
	s_waitcnt vmcnt(4)
	v_pk_fma_f32 v[114:115], v[90:91], v[114:115], v[102:103]
	v_cndmask_b32_e32 v119, v159, v183, vcc
	v_cndmask_b32_e32 v118, v158, v178, vcc
	v_pk_fma_f32 v[112:113], v[94:95], v[112:113], v[114:115]
	v_cndmask_b32_e64 v117, v185, v171, s[42:43]
	v_cndmask_b32_e64 v116, v179, v170, s[42:43]
	v_pk_fma_f32 v[118:119], v[92:93], v[118:119], v[104:105]
	v_pk_fma_f32 v[112:113], v[132:133], v[98:99], v[112:113]
	v_pk_fma_f32 v[116:117], v[96:97], v[116:117], v[118:119]
	v_cndmask_b32_e32 v133, v194, v187, vcc
	v_cndmask_b32_e32 v132, v190, v181, vcc
	v_pk_fma_f32 v[116:117], v[130:131], v[100:101], v[116:117]
	v_cndmask_b32_e64 v131, v189, v195, s[42:43]
	v_cndmask_b32_e64 v130, v184, v191, s[42:43]
	v_pk_fma_f32 v[132:133], v[90:91], v[132:133], v[102:103]
	v_cndmask_b32_e32 v159, v183, v176, vcc
	v_pk_fma_f32 v[130:131], v[94:95], v[130:131], v[132:133]
	v_cndmask_b32_e32 v158, v178, v0, vcc
	v_pk_fma_f32 v[130:131], v[156:157], v[98:99], v[130:131]
	v_cndmask_b32_e64 v157, v177, v185, s[42:43]
	v_cndmask_b32_e64 v156, v107, v179, s[42:43]
	v_pk_fma_f32 v[158:159], v[92:93], v[158:159], v[104:105]
	v_cndmask_b32_e32 v171, v187, v196, vcc
	v_cndmask_b32_e32 v170, v181, v192, vcc
	v_pk_fma_f32 v[156:157], v[96:97], v[156:157], v[158:159]
	v_cndmask_b32_e64 v159, v197, v189, s[42:43]
	v_cndmask_b32_e64 v158, v193, v184, s[42:43]
	v_pk_fma_f32 v[90:91], v[90:91], v[170:171], v[102:103]
	v_cndmask_b32_e32 v103, v176, v186, vcc
	v_pk_fma_f32 v[90:91], v[94:95], v[158:159], v[90:91]
	v_cndmask_b32_e32 v102, v0, v180, vcc
	v_pk_fma_f32 v[90:91], v[122:123], v[98:99], v[90:91]
	v_cndmask_b32_e64 v99, v188, v177, s[42:43]
	v_cndmask_b32_e64 v98, v182, v107, s[42:43]
	v_pk_fma_f32 v[92:93], v[92:93], v[102:103], v[104:105]
	v_pk_fma_f32 v[92:93], v[96:97], v[98:99], v[92:93]
	v_mov_b32_e32 v125, v124
	v_pk_fma_f32 v[92:93], v[120:121], v[100:101], v[92:93]
	v_mov_b32_e32 v129, v128
	v_mov_b32_e32 v98, v124
	v_mov_b32_e32 v99, v124
	v_pk_mul_f32 v[72:73], v[72:73], v[98:99]
	v_pk_mul_f32 v[70:71], v[70:71], v[124:125]
	v_pk_mul_f32 v[66:67], v[66:67], v[128:129]
	s_nop 1
	v_mov_b32_e32 v98, v128
	v_mov_b32_e32 v99, v128
	s_nop 1
	v_mov_b32_dpp v123, v70 row_ror:2 row_mask:0xf bank_mask:0xf
	s_nop 1
	v_mov_b32_dpp v125, v71 row_ror:2 row_mask:0xf bank_mask:0xf
	s_nop 1
	v_mov_b32_dpp v129, v72 row_ror:2 row_mask:0xf bank_mask:0xf
	s_nop 1
	v_mov_b32_dpp v159, v73 row_ror:2 row_mask:0xf bank_mask:0xf
	v_pk_fma_f32 v[134:135], v[134:135], v[100:101], v[156:157]
	v_pk_mul_f32 v[68:69], v[68:69], v[98:99]
	v_mov_b32_dpp v122, v70 row_ror:1 row_mask:0xf bank_mask:0xf
	v_mov_b32_dpp v124, v71 row_ror:1 row_mask:0xf bank_mask:0xf
	v_mov_b32_dpp v128, v72 row_ror:1 row_mask:0xf bank_mask:0xf
	v_mov_b32_dpp v158, v73 row_ror:1 row_mask:0xf bank_mask:0xf
	v_cndmask_b32_e32 v98, v152, v123, vcc
	v_cndmask_b32_e32 v99, v153, v125, vcc
	v_cndmask_b32_e32 v100, v154, v129, vcc
	v_cndmask_b32_e32 v101, v155, v159, vcc
	v_cndmask_b32_e64 v102, v122, v136, s[42:43]
	v_cndmask_b32_e64 v103, v124, v137, s[42:43]
	v_cndmask_b32_e64 v104, v128, v150, s[42:43]
	v_cndmask_b32_e64 v105, v158, v151, s[42:43]
	s_waitcnt vmcnt(1)
	v_pk_fma_f32 v[100:101], v[84:85], v[100:101], v[88:89]
	v_pk_fma_f32 v[98:99], v[82:83], v[98:99], v[86:87]
	v_pk_fma_f32 v[100:101], v[80:81], v[104:105], v[100:101]
	v_pk_fma_f32 v[98:99], v[78:79], v[102:103], v[98:99]
	v_add_u32_e32 v0, 0x90, v106
	v_add_u32_e32 v120, 0xa0, v106
	v_add_u32_e32 v121, 0xb0, v106
	v_pk_mul_f32 v[114:115], v[112:113], s[98:99] op_sel_hi:[1,0]
	v_pk_mul_f32 v[118:119], v[116:117], s[98:99] op_sel_hi:[1,0]
	v_exp_f32_e32 v114, v114
	v_exp_f32_e32 v115, v115
	v_exp_f32_e32 v118, v118
	v_exp_f32_e32 v119, v119
	v_pk_add_f32 v[114:115], v[114:115], 1.0 op_sel_hi:[1,0]
	v_pk_add_f32 v[118:119], v[118:119], 1.0 op_sel_hi:[1,0]
	v_rcp_f32_e32 v114, v114
	v_rcp_f32_e32 v115, v115
	v_rcp_f32_e32 v118, v118
	v_rcp_f32_e32 v119, v119
	v_pk_mul_f32 v[106:107], v[112:113], v[114:115]
	v_pk_mul_f32 v[112:113], v[116:117], v[118:119]
	v_pk_fma_f32 v[72:73], v[72:73], v[76:77], v[100:101]
	v_pk_fma_f32 v[70:71], v[70:71], v[74:75], v[98:99]
	v_pk_mul_f32 v[72:73], v[112:113], v[72:73]
	v_pk_mul_f32 v[70:71], v[106:107], v[70:71]
	v_cvt_pk_bf16_f32 v70, v70, v71
	v_cvt_pk_bf16_f32 v71, v72, v73
	v_mov_b64_e32 v[72:73], s[36:37]
	v_mad_i64_i32 v[98:99], s[0:1], v0, s46, v[72:73]
	v_lshlrev_b64 v[100:101], 1, v[126:127]
	s_nop 1
	v_lshl_add_u64 v[98:99], v[98:99], 0, v[100:101]
	s_nop 1
	v_mov_b32_dpp v114, v66 row_ror:2 row_mask:0xf bank_mask:0xf
	s_nop 1
	v_mov_b32_dpp v116, v67 row_ror:2 row_mask:0xf bank_mask:0xf
	s_nop 1
	v_mov_b32_dpp v118, v68 row_ror:2 row_mask:0xf bank_mask:0xf
	s_nop 1
	v_mov_b32_dpp v126, v69 row_ror:2 row_mask:0xf bank_mask:0xf
	v_mov_b32_e32 v230, v70
	v_mov_b32_e32 v231, v71
	v_mov_b32_dpp v0, v66 row_ror:1 row_mask:0xf bank_mask:0xf
	v_mov_b32_dpp v115, v67 row_ror:1 row_mask:0xf bank_mask:0xf
	v_mov_b32_dpp v117, v68 row_ror:1 row_mask:0xf bank_mask:0xf
	v_mov_b32_dpp v119, v69 row_ror:1 row_mask:0xf bank_mask:0xf
	v_cndmask_b32_e32 v70, v123, v114, vcc
	v_cndmask_b32_e32 v71, v125, v116, vcc
	v_cndmask_b32_e32 v98, v129, v118, vcc
	v_cndmask_b32_e32 v99, v159, v126, vcc
	v_cndmask_b32_e64 v102, v0, v122, s[42:43]
	v_cndmask_b32_e64 v103, v115, v124, s[42:43]
	v_cndmask_b32_e64 v104, v117, v128, s[42:43]
	v_cndmask_b32_e64 v105, v119, v158, s[42:43]
	v_pk_fma_f32 v[98:99], v[84:85], v[98:99], v[88:89]
	v_pk_fma_f32 v[70:71], v[82:83], v[70:71], v[86:87]
	v_pk_fma_f32 v[98:99], v[80:81], v[104:105], v[98:99]
	v_pk_fma_f32 v[70:71], v[78:79], v[102:103], v[70:71]
	v_pk_mul_f32 v[132:133], v[130:131], s[98:99] op_sel_hi:[1,0]
	v_pk_mul_f32 v[156:157], v[134:135], s[98:99] op_sel_hi:[1,0]
	v_exp_f32_e32 v132, v132
	v_exp_f32_e32 v133, v133
	v_exp_f32_e32 v156, v156
	v_exp_f32_e32 v157, v157
	v_pk_add_f32 v[132:133], v[132:133], 1.0 op_sel_hi:[1,0]
	v_pk_add_f32 v[156:157], v[156:157], 1.0 op_sel_hi:[1,0]
	v_rcp_f32_e32 v132, v132
	v_rcp_f32_e32 v133, v133
	v_rcp_f32_e32 v156, v156
	v_rcp_f32_e32 v157, v157
	v_pk_mul_f32 v[106:107], v[130:131], v[132:133]
	v_pk_mul_f32 v[112:113], v[134:135], v[156:157]
	v_pk_fma_f32 v[68:69], v[68:69], v[76:77], v[98:99]
	v_pk_fma_f32 v[66:67], v[66:67], v[74:75], v[70:71]
	v_pk_mul_f32 v[68:69], v[112:113], v[68:69]
	v_pk_mul_f32 v[66:67], v[106:107], v[66:67]
	v_cvt_pk_bf16_f32 v66, v66, v67
	v_cvt_pk_bf16_f32 v67, v68, v69
	v_mad_i64_i32 v[68:69], s[0:1], v120, s46, v[72:73]
	v_lshl_add_u64 v[68:69], v[68:69], 0, v[100:101]
	v_mov_b32_e32 v232, v66
	v_mov_b32_e32 v233, v67
	s_nop 1
	s_nop 1
	v_mov_b32_dpp v66, v110 row_ror:2 row_mask:0xf bank_mask:0xf
	s_nop 1
	v_mov_b32_dpp v67, v111 row_ror:2 row_mask:0xf bank_mask:0xf
	s_nop 1
	v_mov_b32_dpp v68, v108 row_ror:2 row_mask:0xf bank_mask:0xf
	s_nop 1
	v_mov_b32_dpp v69, v109 row_ror:2 row_mask:0xf bank_mask:0xf
	v_mov_b32_dpp v70, v110 row_ror:1 row_mask:0xf bank_mask:0xf
	v_mov_b32_dpp v71, v111 row_ror:1 row_mask:0xf bank_mask:0xf
	v_mov_b32_dpp v98, v108 row_ror:1 row_mask:0xf bank_mask:0xf
	v_mov_b32_dpp v99, v109 row_ror:1 row_mask:0xf bank_mask:0xf
	v_cndmask_b32_e32 v66, v114, v66, vcc
	v_cndmask_b32_e32 v67, v116, v67, vcc
	v_cndmask_b32_e32 v68, v118, v68, vcc
	v_cndmask_b32_e32 v69, v126, v69, vcc
	v_cndmask_b32_e64 v70, v70, v0, s[42:43]
	v_cndmask_b32_e64 v71, v71, v115, s[42:43]
	v_cndmask_b32_e64 v98, v98, v117, s[42:43]
	v_cndmask_b32_e64 v99, v99, v119, s[42:43]
	v_pk_fma_f32 v[66:67], v[82:83], v[66:67], v[86:87]
	v_pk_fma_f32 v[68:69], v[84:85], v[68:69], v[88:89]
	v_pk_fma_f32 v[66:67], v[78:79], v[70:71], v[66:67]
	v_pk_fma_f32 v[68:69], v[80:81], v[98:99], v[68:69]
	v_pk_mul_f32 v[94:95], v[90:91], s[98:99] op_sel_hi:[1,0]
	v_pk_mul_f32 v[96:97], v[92:93], s[98:99] op_sel_hi:[1,0]
	v_exp_f32_e32 v94, v94
	v_exp_f32_e32 v95, v95
	v_exp_f32_e32 v96, v96
	v_exp_f32_e32 v97, v97
	v_pk_add_f32 v[94:95], v[94:95], 1.0 op_sel_hi:[1,0]
	v_pk_add_f32 v[96:97], v[96:97], 1.0 op_sel_hi:[1,0]
	v_rcp_f32_e32 v94, v94
	v_rcp_f32_e32 v95, v95
	v_rcp_f32_e32 v96, v96
	v_rcp_f32_e32 v97, v97
	v_pk_mul_f32 v[90:91], v[90:91], v[94:95]
	v_pk_mul_f32 v[92:93], v[92:93], v[96:97]
	v_pk_fma_f32 v[66:67], v[110:111], v[74:75], v[66:67]
	v_pk_fma_f32 v[68:69], v[108:109], v[76:77], v[68:69]
	v_pk_mul_f32 v[66:67], v[90:91], v[66:67]
	v_pk_mul_f32 v[68:69], v[92:93], v[68:69]
	v_cvt_pk_bf16_f32 v66, v66, v67
	s_nop 0
	v_cvt_pk_bf16_f32 v67, v68, v69
	v_mad_i64_i32 v[68:69], s[0:1], v121, s46, v[72:73]
	v_lshl_add_u64 v[68:69], v[68:69], 0, v[100:101]
	v_mov_b32_e32 v234, v66
	v_mov_b32_e32 v235, v67
	s_nop 0
	v_and_b32_e32 v97, 15, v226
	v_or_b32_e32 v74, s4, v97
	v_ashrrev_i32_e32 v75, 31, v74
	v_lshl_add_u64 v[72:73], v[74:75], 3, s[38:39]
	global_load_dwordx2 v[76:77], v[72:73], off
	global_load_dwordx2 v[70:71], v[72:73], off offset:128
	global_load_dwordx2 v[68:69], v[72:73], off offset:256
	s_nop 0
	global_load_dwordx2 v[72:73], v[72:73], off offset:384
	v_ashrrev_i32_e32 v0, 1, v226
	v_and_b32_e32 v0, -8, v0
	v_add_u32_e32 v66, s21, v0
	s_waitcnt vmcnt(3)
	v_ffbh_u32_e32 v0, v77
	v_min_u32_e32 v0, 32, v0
	v_lshlrev_b64 v[76:77], v0, v[76:77]
	v_min_u32_e32 v67, 1, v76
	v_or_b32_e32 v67, v77, v67
	v_cvt_f32_u32_e32 v67, v67
	v_sub_u32_e32 v0, 32, v0
	v_ldexp_f32 v0, v67, v0
	v_fmamk_f32 v0, v0, 0x2e800000, v210
	s_nop 0
	v_rsq_f32_e32 v0, v0
	s_nop 0
	s_nop 0
	v_ashrrev_i32_e32 v67, 31, v66
	v_pk_mul_f32 v[92:93], v[64:65], v[0:1] op_sel_hi:[1,0]
	v_pk_mul_f32 v[90:91], v[62:63], v[0:1] op_sel_hi:[1,0]
	v_pk_mul_f32 v[86:87], v[60:61], v[0:1] op_sel_hi:[1,0]
	v_pk_mul_f32 v[88:89], v[58:59], v[0:1] op_sel_hi:[1,0]
	v_lshl_add_u64 v[58:59], v[66:67], 1, s[76:77]
	v_cmp_gt_u32_e32 vcc, 2, v97
	s_and_saveexec_b64 s[0:1], vcc
	s_cbranch_execz .LBB0_123
	v_mul_u32_u24_e32 v0, 0x1600, v97
	v_lshlrev_b32_e32 v0, 1, v0
	v_cvt_pk_bf16_f32 v60, v90, v91
	v_cvt_pk_bf16_f32 v61, v92, v93
	v_lshl_add_u64 v[64:65], v[58:59], 0, v[0:1]
	v_cvt_pk_bf16_f32 v62, v88, v89
	v_cvt_pk_bf16_f32 v63, v86, v87
	global_store_dwordx2 v[64:65], v[60:61], off offset:8
	global_store_dwordx2 v[64:65], v[62:63], off offset:264

.LBB0_125:
	s_or_b64 exec, exec, s[0:1]
	v_ffbh_u32_e32 v0, v71
	v_min_u32_e32 v0, 32, v0
	v_lshlrev_b64 v[50:51], v0, v[70:71]
	v_min_u32_e32 v50, 1, v50
	v_or_b32_e32 v50, v51, v50
	v_cvt_f32_u32_e32 v50, v50
	v_sub_u32_e32 v0, 32, v0
	s_or_b32 s5, s5, 4
	v_add_u32_e32 v94, s5, v66
	v_ldexp_f32 v0, v50, v0
	v_fmamk_f32 v0, v0, 0x2e800000, v210
	s_nop 0
	v_rsq_f32_e32 v0, v0
	s_nop 0
	s_nop 0
	v_mov_b32_e32 v84, v0
	v_ffbh_u32_e32 v0, v69
	v_min_u32_e32 v0, 32, v0
	v_pk_mul_f32 v[100:101], v[46:47], v[84:85] op_sel_hi:[1,0]
	v_lshlrev_b64 v[46:47], v0, v[68:69]
	v_min_u32_e32 v46, 1, v46
	v_or_b32_e32 v46, v47, v46
	v_cvt_f32_u32_e32 v46, v46
	v_sub_u32_e32 v0, 32, v0
	v_pk_mul_f32 v[98:99], v[48:49], v[84:85] op_sel_hi:[1,0]
	v_ldexp_f32 v0, v46, v0
	v_fmamk_f32 v0, v0, 0x2e800000, v210
	s_nop 0
	v_rsq_f32_e32 v0, v0
	s_nop 0
	s_nop 0
	v_mov_b32_e32 v96, v0
	v_pk_mul_f32 v[102:103], v[44:45], v[96:97] op_sel_hi:[1,0]
	v_pk_mul_f32 v[112:113], v[42:43], v[96:97] op_sel_hi:[1,0]
	v_ashrrev_i32_e32 v95, 31, v94
	v_lshlrev_b64 v[54:55], 2, v[94:95]
	v_lshl_add_u64 v[42:43], s[44:45], 0, v[54:55]
	v_lshl_add_u64 v[44:45], s[60:61], 0, v[54:55]
	global_load_dwordx4 v[58:61], v[42:43], off
	global_load_dwordx4 v[62:65], v[44:45], off
	v_lshl_add_u64 v[42:43], s[2:3], 0, v[54:55]
	global_load_dwordx4 v[66:69], v[42:43], off
	v_lshl_add_u64 v[42:43], s[48:49], 0, v[54:55]
	global_load_dwordx4 v[70:73], v[42:43], off
	s_nop 1
	v_cmp_lt_u32_e32 vcc, 1, v97
	v_mov_b32_dpp v120, v90 row_ror:1 row_mask:0xf bank_mask:0xf
	v_mov_b32_dpp v118, v90 row_ror:2 row_mask:0xf bank_mask:0xf
	v_mov_b32_dpp v121, v91 row_ror:1 row_mask:0xf bank_mask:0xf
	v_mov_b32_dpp v119, v91 row_ror:2 row_mask:0xf bank_mask:0xf
	v_mov_b32_dpp v116, v92 row_ror:1 row_mask:0xf bank_mask:0xf
	v_mov_b32_dpp v114, v92 row_ror:2 row_mask:0xf bank_mask:0xf
	v_mov_b32_dpp v117, v93 row_ror:1 row_mask:0xf bank_mask:0xf
	v_mov_b32_dpp v115, v93 row_ror:2 row_mask:0xf bank_mask:0xf
	v_mov_b32_dpp v137, v100 row_ror:1 row_mask:0xf bank_mask:0xf
	v_mov_b32_dpp v136, v100 row_ror:2 row_mask:0xf bank_mask:0xf
	v_mov_b32_dpp v153, v101 row_ror:1 row_mask:0xf bank_mask:0xf
	v_mov_b32_dpp v152, v101 row_ror:2 row_mask:0xf bank_mask:0xf
	v_mov_b32_dpp v125, v98 row_ror:1 row_mask:0xf bank_mask:0xf
	v_mov_b32_dpp v124, v98 row_ror:2 row_mask:0xf bank_mask:0xf
	v_mov_b32_dpp v131, v99 row_ror:1 row_mask:0xf bank_mask:0xf
	v_mov_b32_dpp v129, v99 row_ror:2 row_mask:0xf bank_mask:0xf
	v_mov_b32_dpp v130, v112 row_ror:1 row_mask:0xf bank_mask:0xf
	v_mov_b32_dpp v127, v112 row_ror:2 row_mask:0xf bank_mask:0xf
	v_mov_b32_dpp v135, v113 row_ror:1 row_mask:0xf bank_mask:0xf
	v_mov_b32_dpp v133, v113 row_ror:2 row_mask:0xf bank_mask:0xf
	v_mov_b32_dpp v75, v102 row_ror:1 row_mask:0xf bank_mask:0xf
	v_mov_b32_dpp v0, v102 row_ror:2 row_mask:0xf bank_mask:0xf
	v_mov_b32_dpp v123, v103 row_ror:1 row_mask:0xf bank_mask:0xf
	v_mov_b32_dpp v122, v103 row_ror:2 row_mask:0xf bank_mask:0xf
	v_mov_b32_dpp v151, v82 row_ror:1 row_mask:0xf bank_mask:0xf
	v_mov_b32_dpp v150, v82 row_ror:2 row_mask:0xf bank_mask:0xf
	v_mov_b32_dpp v155, v83 row_ror:1 row_mask:0xf bank_mask:0xf
	v_mov_b32_dpp v154, v83 row_ror:2 row_mask:0xf bank_mask:0xf
	v_mov_b32_dpp v128, v80 row_ror:1 row_mask:0xf bank_mask:0xf
	v_mov_b32_dpp v126, v80 row_ror:2 row_mask:0xf bank_mask:0xf
	v_mov_b32_dpp v134, v81 row_ror:1 row_mask:0xf bank_mask:0xf
	v_mov_b32_dpp v132, v81 row_ror:2 row_mask:0xf bank_mask:0xf
	v_lshl_add_u64 v[42:43], s[96:97], 0, v[54:55]
	v_lshl_add_u64 v[44:45], s[62:63], 0, v[54:55]
	global_load_dwordx4 v[50:53], v[42:43], off
	global_load_dwordx4 v[46:49], v[44:45], off
	v_lshl_add_u64 v[42:43], s[64:65], 0, v[54:55]
	v_lshl_add_u64 v[54:55], s[66:67], 0, v[54:55]
	global_load_dwordx4 v[42:45], v[42:43], off
	s_nop 1
	global_load_dwordx4 v[54:57], v[54:55], off
	s_nop 1
	v_mov_b32_dpp v104, v88 row_ror:1 row_mask:0xf bank_mask:0xf
	v_mov_b32_dpp v108, v88 row_ror:2 row_mask:0xf bank_mask:0xf
	v_mov_b32_dpp v105, v89 row_ror:1 row_mask:0xf bank_mask:0xf
	v_mov_b32_dpp v109, v89 row_ror:2 row_mask:0xf bank_mask:0xf
	v_mov_b32_dpp v106, v86 row_ror:1 row_mask:0xf bank_mask:0xf
	v_mov_b32_dpp v110, v86 row_ror:2 row_mask:0xf bank_mask:0xf
	v_mov_b32_dpp v107, v87 row_ror:1 row_mask:0xf bank_mask:0xf
	v_mov_b32_dpp v111, v87 row_ror:2 row_mask:0xf bank_mask:0xf
	s_and_saveexec_b64 s[0:1], vcc
	s_cbranch_execz .Lcg_skip2
	s_waitcnt vmcnt(4)
	v_pk_fma_f32 v[156:157], v[60:61], v[114:115], v[72:73]
	s_nop 0
	v_pk_fma_f32 v[156:157], v[64:65], v[116:117], v[156:157]
	s_nop 0
	v_pk_fma_f32 v[92:93], v[92:93], v[68:69], v[156:157]
	v_pk_fma_f32 v[156:157], v[58:59], v[118:119], v[70:71]
	v_pk_fma_f32 v[156:157], v[62:63], v[120:121], v[156:157]
	v_pk_fma_f32 v[90:91], v[90:91], v[66:67], v[156:157]
	v_pk_mul_f32 v[156:157], v[90:91], s[98:99] op_sel_hi:[1,0]
	v_pk_mul_f32 v[158:159], v[92:93], s[98:99] op_sel_hi:[1,0]
	v_exp_f32_e32 v156, v156
	v_exp_f32_e32 v157, v157
	v_exp_f32_e32 v158, v158
	v_exp_f32_e32 v159, v159
	v_pk_add_f32 v[156:157], v[156:157], 1.0 op_sel_hi:[1,0]
	v_pk_add_f32 v[158:159], v[158:159], 1.0 op_sel_hi:[1,0]
	v_rcp_f32_e32 v156, v156
	v_rcp_f32_e32 v157, v157
	v_rcp_f32_e32 v158, v158
	v_rcp_f32_e32 v159, v159
	v_pk_mul_f32 v[90:91], v[90:91], v[156:157]
	v_pk_mul_f32 v[92:93], v[92:93], v[158:159]
	s_waitcnt vmcnt(0)
	v_pk_fma_f32 v[156:157], v[52:53], v[110:111], v[56:57]
	v_pk_fma_f32 v[158:159], v[50:51], v[108:109], v[54:55]
	v_pk_fma_f32 v[156:157], v[48:49], v[106:107], v[156:157]
	v_pk_fma_f32 v[158:159], v[46:47], v[104:105], v[158:159]
	v_pk_fma_f32 v[86:87], v[86:87], v[44:45], v[156:157]
	v_pk_fma_f32 v[88:89], v[88:89], v[42:43], v[158:159]
	v_pk_mul_f32 v[86:87], v[92:93], v[86:87]
	v_pk_mul_f32 v[88:89], v[90:91], v[88:89]
	s_nop 0
	v_cvt_pk_bf16_f32 v88, v88, v89
	v_cvt_pk_bf16_f32 v89, v86, v87
	v_mov_b64_e32 v[86:87], s[36:37]
	v_mad_i64_i32 v[86:87], s[6:7], v74, s46, v[86:87]
	v_lshl_add_u64 v[86:87], v[94:95], 1, v[86:87]
	v_mov_b32_e32 v236, v248
	v_mov_b32_e32 v237, v249
	v_mov_b32_e32 v238, v88
	v_mov_b32_e32 v239, v89
	global_store_dwordx4 v[86:87], v[236:239], off offset:-8
.LBB0_127:
	s_or_b64 exec, exec, s[0:1]
	v_cmp_eq_u32_e64 s[42:43], 0, v97
	v_cndmask_b32_e32 v89, v119, v152, vcc
	v_cndmask_b32_e32 v88, v118, v136, vcc
	v_cndmask_b32_e64 v87, v153, v121, s[42:43]
	v_cndmask_b32_e64 v86, v137, v120, s[42:43]
	s_waitcnt vmcnt(4)
	v_pk_fma_f32 v[88:89], v[58:59], v[88:89], v[70:71]
	v_cndmask_b32_e32 v93, v115, v129, vcc
	v_cndmask_b32_e32 v92, v114, v124, vcc
	v_pk_fma_f32 v[86:87], v[62:63], v[86:87], v[88:89]
	v_cndmask_b32_e64 v91, v131, v117, s[42:43]
	v_cndmask_b32_e64 v90, v125, v116, s[42:43]
	v_pk_fma_f32 v[92:93], v[60:61], v[92:93], v[72:73]
	v_pk_fma_f32 v[86:87], v[100:101], v[66:67], v[86:87]
	v_pk_fma_f32 v[90:91], v[64:65], v[90:91], v[92:93]
	v_cndmask_b32_e32 v101, v152, v133, vcc
	v_cndmask_b32_e32 v100, v136, v127, vcc
	v_pk_fma_f32 v[90:91], v[98:99], v[68:69], v[90:91]
	v_cndmask_b32_e64 v99, v135, v153, s[42:43]
	v_cndmask_b32_e64 v98, v130, v137, s[42:43]
	v_pk_fma_f32 v[100:101], v[58:59], v[100:101], v[70:71]
	v_cndmask_b32_e32 v115, v129, v122, vcc
	v_pk_fma_f32 v[98:99], v[62:63], v[98:99], v[100:101]
	v_cndmask_b32_e32 v114, v124, v0, vcc
	v_pk_fma_f32 v[98:99], v[112:113], v[66:67], v[98:99]
	v_cndmask_b32_e64 v113, v123, v131, s[42:43]
	v_cndmask_b32_e64 v112, v75, v125, s[42:43]
	v_pk_fma_f32 v[114:115], v[60:61], v[114:115], v[72:73]
	v_cndmask_b32_e32 v117, v133, v154, vcc
	v_cndmask_b32_e32 v116, v127, v150, vcc
	v_pk_fma_f32 v[112:113], v[64:65], v[112:113], v[114:115]
	v_cndmask_b32_e64 v115, v155, v135, s[42:43]
	v_cndmask_b32_e64 v114, v151, v130, s[42:43]
	v_pk_fma_f32 v[58:59], v[58:59], v[116:117], v[70:71]
	v_cndmask_b32_e32 v71, v122, v132, vcc
	v_pk_fma_f32 v[58:59], v[62:63], v[114:115], v[58:59]
	v_cndmask_b32_e32 v70, v0, v126, vcc
	v_pk_fma_f32 v[58:59], v[82:83], v[66:67], v[58:59]
	v_cndmask_b32_e64 v67, v134, v123, s[42:43]
	v_cndmask_b32_e64 v66, v128, v75, s[42:43]
	v_pk_fma_f32 v[60:61], v[60:61], v[70:71], v[72:73]
	v_pk_fma_f32 v[60:61], v[64:65], v[66:67], v[60:61]
	v_mov_b32_e32 v85, v84
	v_pk_fma_f32 v[60:61], v[80:81], v[68:69], v[60:61]
	v_mov_b32_e32 v97, v96
	v_mov_b32_e32 v66, v84
	v_mov_b32_e32 v67, v84
	v_pk_mul_f32 v[40:41], v[40:41], v[66:67]
	v_pk_mul_f32 v[38:39], v[38:39], v[84:85]
	v_pk_mul_f32 v[34:35], v[34:35], v[96:97]
	s_nop 1
	v_mov_b32_e32 v66, v96
	v_mov_b32_e32 v67, v96
	s_nop 1
	v_mov_b32_dpp v85, v38 row_ror:2 row_mask:0xf bank_mask:0xf
	s_nop 1
	v_mov_b32_dpp v97, v39 row_ror:2 row_mask:0xf bank_mask:0xf
	s_nop 1
	v_mov_b32_dpp v115, v40 row_ror:2 row_mask:0xf bank_mask:0xf
	s_nop 1
	v_mov_b32_dpp v117, v41 row_ror:2 row_mask:0xf bank_mask:0xf
	v_pk_fma_f32 v[102:103], v[102:103], v[68:69], v[112:113]
	v_pk_mul_f32 v[36:37], v[36:37], v[66:67]
	v_mov_b32_dpp v84, v38 row_ror:1 row_mask:0xf bank_mask:0xf
	v_mov_b32_dpp v96, v39 row_ror:1 row_mask:0xf bank_mask:0xf
	v_mov_b32_dpp v114, v40 row_ror:1 row_mask:0xf bank_mask:0xf
	v_mov_b32_dpp v116, v41 row_ror:1 row_mask:0xf bank_mask:0xf
	v_cndmask_b32_e32 v66, v108, v85, vcc
	v_cndmask_b32_e32 v67, v109, v97, vcc
	v_cndmask_b32_e32 v68, v110, v115, vcc
	v_cndmask_b32_e32 v69, v111, v117, vcc
	v_cndmask_b32_e64 v70, v84, v104, s[42:43]
	v_cndmask_b32_e64 v71, v96, v105, s[42:43]
	v_cndmask_b32_e64 v72, v114, v106, s[42:43]
	v_cndmask_b32_e64 v73, v116, v107, s[42:43]
	s_waitcnt vmcnt(1)
	v_pk_fma_f32 v[68:69], v[52:53], v[68:69], v[56:57]
	v_pk_fma_f32 v[66:67], v[50:51], v[66:67], v[54:55]
	v_pk_fma_f32 v[68:69], v[48:49], v[72:73], v[68:69]
	v_pk_fma_f32 v[66:67], v[46:47], v[70:71], v[66:67]
	v_or_b32_e32 v0, 16, v74
	v_or_b32_e32 v82, 32, v74
	v_or_b32_e32 v83, 48, v74
	v_pk_mul_f32 v[88:89], v[86:87], s[98:99] op_sel_hi:[1,0]
	v_pk_mul_f32 v[92:93], v[90:91], s[98:99] op_sel_hi:[1,0]
	v_exp_f32_e32 v88, v88
	v_exp_f32_e32 v89, v89
	v_exp_f32_e32 v92, v92
	v_exp_f32_e32 v93, v93
	v_pk_add_f32 v[88:89], v[88:89], 1.0 op_sel_hi:[1,0]
	v_pk_add_f32 v[92:93], v[92:93], 1.0 op_sel_hi:[1,0]
	v_rcp_f32_e32 v88, v88
	v_rcp_f32_e32 v89, v89
	v_rcp_f32_e32 v92, v92
	v_rcp_f32_e32 v93, v93
	v_pk_mul_f32 v[74:75], v[86:87], v[88:89]
	v_pk_mul_f32 v[80:81], v[90:91], v[92:93]
	v_pk_fma_f32 v[40:41], v[40:41], v[44:45], v[68:69]
	v_pk_fma_f32 v[38:39], v[38:39], v[42:43], v[66:67]
	v_pk_mul_f32 v[40:41], v[80:81], v[40:41]
	v_pk_mul_f32 v[38:39], v[74:75], v[38:39]
	v_cvt_pk_bf16_f32 v38, v38, v39
	v_cvt_pk_bf16_f32 v39, v40, v41
	v_mov_b64_e32 v[40:41], s[36:37]
	v_mad_i64_i32 v[66:67], s[0:1], v0, s46, v[40:41]
	v_lshlrev_b64 v[68:69], 1, v[94:95]
	s_nop 1
	v_lshl_add_u64 v[66:67], v[66:67], 0, v[68:69]
	s_nop 1
	v_mov_b32_dpp v86, v34 row_ror:2 row_mask:0xf bank_mask:0xf
	s_nop 1
	v_mov_b32_dpp v88, v35 row_ror:2 row_mask:0xf bank_mask:0xf
	s_nop 1
	v_mov_b32_dpp v90, v36 row_ror:2 row_mask:0xf bank_mask:0xf
	s_nop 1
	v_mov_b32_dpp v92, v37 row_ror:2 row_mask:0xf bank_mask:0xf
	v_mov_b32_e32 v236, v250
	v_mov_b32_e32 v237, v251
	v_mov_b32_e32 v238, v38
	v_mov_b32_e32 v239, v39
	global_store_dwordx4 v[66:67], v[236:239], off offset:-8
	v_mov_b32_dpp v0, v34 row_ror:1 row_mask:0xf bank_mask:0xf
	v_mov_b32_dpp v87, v35 row_ror:1 row_mask:0xf bank_mask:0xf
	v_mov_b32_dpp v89, v36 row_ror:1 row_mask:0xf bank_mask:0xf
	v_mov_b32_dpp v91, v37 row_ror:1 row_mask:0xf bank_mask:0xf
	v_cndmask_b32_e32 v38, v85, v86, vcc
	v_cndmask_b32_e32 v39, v97, v88, vcc
	v_cndmask_b32_e32 v66, v115, v90, vcc
	v_cndmask_b32_e32 v67, v117, v92, vcc
	v_cndmask_b32_e64 v70, v0, v84, s[42:43]
	v_cndmask_b32_e64 v71, v87, v96, s[42:43]
	v_cndmask_b32_e64 v72, v89, v114, s[42:43]
	v_cndmask_b32_e64 v73, v91, v116, s[42:43]
	v_pk_fma_f32 v[66:67], v[52:53], v[66:67], v[56:57]
	v_pk_fma_f32 v[38:39], v[50:51], v[38:39], v[54:55]
	v_pk_fma_f32 v[66:67], v[48:49], v[72:73], v[66:67]
	v_pk_fma_f32 v[38:39], v[46:47], v[70:71], v[38:39]
	v_pk_mul_f32 v[100:101], v[98:99], s[98:99] op_sel_hi:[1,0]
	v_pk_mul_f32 v[112:113], v[102:103], s[98:99] op_sel_hi:[1,0]
	v_exp_f32_e32 v100, v100
	v_exp_f32_e32 v101, v101
	v_exp_f32_e32 v112, v112
	v_exp_f32_e32 v113, v113
	v_pk_add_f32 v[100:101], v[100:101], 1.0 op_sel_hi:[1,0]
	v_pk_add_f32 v[112:113], v[112:113], 1.0 op_sel_hi:[1,0]
	v_rcp_f32_e32 v100, v100
	v_rcp_f32_e32 v101, v101
	v_rcp_f32_e32 v112, v112
	v_rcp_f32_e32 v113, v113
	v_pk_mul_f32 v[74:75], v[98:99], v[100:101]
	v_pk_mul_f32 v[80:81], v[102:103], v[112:113]
	v_pk_fma_f32 v[36:37], v[36:37], v[44:45], v[66:67]
	v_pk_fma_f32 v[34:35], v[34:35], v[42:43], v[38:39]
	v_pk_mul_f32 v[36:37], v[80:81], v[36:37]
	v_pk_mul_f32 v[34:35], v[74:75], v[34:35]
	v_cvt_pk_bf16_f32 v34, v34, v35
	v_cvt_pk_bf16_f32 v35, v36, v37
	v_mad_i64_i32 v[36:37], s[0:1], v82, s46, v[40:41]
	v_lshl_add_u64 v[36:37], v[36:37], 0, v[68:69]
	v_mov_b32_e32 v236, v244
	v_mov_b32_e32 v237, v245
	v_mov_b32_e32 v238, v34
	v_mov_b32_e32 v239, v35
	global_store_dwordx4 v[36:37], v[236:239], off offset:-8
	s_nop 1
	s_nop 1
	v_mov_b32_dpp v34, v78 row_ror:2 row_mask:0xf bank_mask:0xf
	s_nop 1
	v_mov_b32_dpp v35, v79 row_ror:2 row_mask:0xf bank_mask:0xf
	s_nop 1
	v_mov_b32_dpp v36, v76 row_ror:2 row_mask:0xf bank_mask:0xf
	s_nop 1
	v_mov_b32_dpp v37, v77 row_ror:2 row_mask:0xf bank_mask:0xf
	v_mov_b32_dpp v38, v78 row_ror:1 row_mask:0xf bank_mask:0xf
	v_mov_b32_dpp v39, v79 row_ror:1 row_mask:0xf bank_mask:0xf
	v_mov_b32_dpp v66, v76 row_ror:1 row_mask:0xf bank_mask:0xf
	v_mov_b32_dpp v67, v77 row_ror:1 row_mask:0xf bank_mask:0xf
	v_cndmask_b32_e32 v34, v86, v34, vcc
	v_cndmask_b32_e32 v35, v88, v35, vcc
	v_cndmask_b32_e32 v36, v90, v36, vcc
	v_cndmask_b32_e32 v37, v92, v37, vcc
	v_cndmask_b32_e64 v38, v38, v0, s[42:43]
	v_cndmask_b32_e64 v39, v39, v87, s[42:43]
	v_cndmask_b32_e64 v66, v66, v89, s[42:43]
	v_cndmask_b32_e64 v67, v67, v91, s[42:43]
	v_pk_fma_f32 v[34:35], v[50:51], v[34:35], v[54:55]
	v_pk_fma_f32 v[36:37], v[52:53], v[36:37], v[56:57]
	v_pk_fma_f32 v[34:35], v[46:47], v[38:39], v[34:35]
	v_pk_fma_f32 v[36:37], v[48:49], v[66:67], v[36:37]
	v_pk_mul_f32 v[62:63], v[58:59], s[98:99] op_sel_hi:[1,0]
	v_pk_mul_f32 v[64:65], v[60:61], s[98:99] op_sel_hi:[1,0]
	v_exp_f32_e32 v62, v62
	v_exp_f32_e32 v63, v63
	v_exp_f32_e32 v64, v64
	v_exp_f32_e32 v65, v65
	v_pk_add_f32 v[62:63], v[62:63], 1.0 op_sel_hi:[1,0]
	v_pk_add_f32 v[64:65], v[64:65], 1.0 op_sel_hi:[1,0]
	v_rcp_f32_e32 v62, v62
	v_rcp_f32_e32 v63, v63
	v_rcp_f32_e32 v64, v64
	v_rcp_f32_e32 v65, v65
	v_pk_mul_f32 v[58:59], v[58:59], v[62:63]
	v_pk_mul_f32 v[60:61], v[60:61], v[64:65]
	v_pk_fma_f32 v[34:35], v[78:79], v[42:43], v[34:35]
	v_pk_fma_f32 v[36:37], v[76:77], v[44:45], v[36:37]
	v_pk_mul_f32 v[34:35], v[58:59], v[34:35]
	v_pk_mul_f32 v[36:37], v[60:61], v[36:37]
	v_cvt_pk_bf16_f32 v34, v34, v35
	s_nop 0
	v_cvt_pk_bf16_f32 v35, v36, v37
	v_mad_i64_i32 v[36:37], s[0:1], v83, s46, v[40:41]
	v_lshl_add_u64 v[36:37], v[36:37], 0, v[68:69]
	v_mov_b32_e32 v236, v246
	v_mov_b32_e32 v237, v247
	v_mov_b32_e32 v238, v34
	v_mov_b32_e32 v239, v35
	global_store_dwordx4 v[36:37], v[236:239], off offset:-8
	s_nop 0
	v_and_b32_e32 v108, 15, v226
	v_or_b32_e32 v56, s4, v108
	v_ashrrev_i32_e32 v57, 31, v56
	v_lshl_add_u64 v[40:41], v[56:57], 3, s[38:39]
	global_load_dwordx2 v[42:43], v[40:41], off offset:1024
	global_load_dwordx2 v[38:39], v[40:41], off offset:1152
	global_load_dwordx2 v[36:37], v[40:41], off offset:1280
	s_nop 0
	global_load_dwordx2 v[40:41], v[40:41], off offset:1408
	v_ashrrev_i32_e32 v0, 1, v226
	v_and_b32_e32 v0, -8, v0
	v_add_u32_e32 v34, s21, v0
	s_waitcnt vmcnt(3)
	v_ffbh_u32_e32 v0, v43
	v_min_u32_e32 v0, 32, v0
	v_lshlrev_b64 v[42:43], v0, v[42:43]
	v_min_u32_e32 v35, 1, v42
	v_or_b32_e32 v35, v43, v35
	v_cvt_f32_u32_e32 v35, v35
	v_sub_u32_e32 v0, 32, v0
	v_ldexp_f32 v0, v35, v0
	v_fmamk_f32 v0, v0, 0x2e800000, v210
	s_nop 0
	v_rsq_f32_e32 v0, v0
	s_nop 0
	s_nop 0
	v_ashrrev_i32_e32 v35, 31, v34
	v_pk_mul_f32 v[84:85], v[32:33], v[0:1] op_sel_hi:[1,0]
	v_pk_mul_f32 v[44:45], v[30:31], v[0:1] op_sel_hi:[1,0]
	v_pk_mul_f32 v[72:73], v[28:29], v[0:1] op_sel_hi:[1,0]
	v_pk_mul_f32 v[42:43], v[26:27], v[0:1] op_sel_hi:[1,0]
	v_lshl_add_u64 v[26:27], v[34:35], 1, s[78:79]
	v_cmp_gt_u32_e32 vcc, 2, v108
	s_and_saveexec_b64 s[0:1], vcc
	s_cbranch_execz .LBB0_129
	v_mul_u32_u24_e32 v0, 0x1600, v108
	v_lshlrev_b32_e32 v0, 1, v0
	v_cvt_pk_bf16_f32 v28, v44, v45
	v_cvt_pk_bf16_f32 v29, v84, v85
	v_lshl_add_u64 v[32:33], v[26:27], 0, v[0:1]
	v_cvt_pk_bf16_f32 v30, v42, v43
	v_cvt_pk_bf16_f32 v31, v72, v73
	global_store_dwordx2 v[32:33], v[28:29], off offset:8
	global_store_dwordx2 v[32:33], v[30:31], off offset:264

.LBB0_131:
	s_or_b64 exec, exec, s[0:1]
	v_ffbh_u32_e32 v0, v39
	v_min_u32_e32 v0, 32, v0
	v_lshlrev_b64 v[14:15], v0, v[38:39]
	v_min_u32_e32 v14, 1, v14
	v_or_b32_e32 v14, v15, v14
	v_cvt_f32_u32_e32 v14, v14
	v_sub_u32_e32 v0, 32, v0
	v_add_u32_e32 v58, s5, v34
	v_ldexp_f32 v0, v14, v0
	v_fmamk_f32 v0, v0, 0x2e800000, v210
	s_nop 0
	v_rsq_f32_e32 v0, v0
	s_nop 0
	s_nop 0
	v_mov_b32_e32 v52, v0
	v_ffbh_u32_e32 v0, v37
	v_min_u32_e32 v0, 32, v0
	v_lshlrev_b64 v[14:15], v0, v[36:37]
	v_min_u32_e32 v14, 1, v14
	v_or_b32_e32 v14, v15, v14
	v_cvt_f32_u32_e32 v14, v14
	v_sub_u32_e32 v0, 32, v0
	v_pk_mul_f32 v[60:61], v[20:21], v[52:53] op_sel_hi:[1,0]
	v_pk_mul_f32 v[54:55], v[18:19], v[52:53] op_sel_hi:[1,0]
	v_ldexp_f32 v0, v14, v0
	v_fmamk_f32 v0, v0, 0x2e800000, v210
	s_nop 0
	v_rsq_f32_e32 v0, v0
	s_nop 0
	s_nop 0
	v_mov_b32_e32 v62, v0
	v_pk_mul_f32 v[88:89], v[12:13], v[62:63] op_sel_hi:[1,0]
	v_pk_mul_f32 v[82:83], v[10:11], v[62:63] op_sel_hi:[1,0]
	v_ashrrev_i32_e32 v59, 31, v58
	v_lshlrev_b64 v[22:23], 2, v[58:59]
	v_lshl_add_u64 v[10:11], s[44:45], 0, v[22:23]
	v_lshl_add_u64 v[12:13], s[60:61], 0, v[22:23]
	global_load_dwordx4 v[26:29], v[10:11], off
	global_load_dwordx4 v[30:33], v[12:13], off
	v_lshl_add_u64 v[10:11], s[2:3], 0, v[22:23]
	global_load_dwordx4 v[34:37], v[10:11], off
	v_lshl_add_u64 v[10:11], s[48:49], 0, v[22:23]
	global_load_dwordx4 v[38:41], v[10:11], off
	s_nop 1
	v_cmp_lt_u32_e32 vcc, 1, v108
	v_mov_b32_dpp v66, v44 row_ror:1 row_mask:0xf bank_mask:0xf
	v_mov_b32_dpp v87, v44 row_ror:2 row_mask:0xf bank_mask:0xf
	v_mov_b32_dpp v67, v45 row_ror:1 row_mask:0xf bank_mask:0xf
	v_mov_b32_dpp v86, v45 row_ror:2 row_mask:0xf bank_mask:0xf
	v_mov_b32_dpp v80, v84 row_ror:1 row_mask:0xf bank_mask:0xf
	v_mov_b32_dpp v91, v84 row_ror:2 row_mask:0xf bank_mask:0xf
	v_mov_b32_dpp v81, v85 row_ror:1 row_mask:0xf bank_mask:0xf
	v_mov_b32_dpp v90, v85 row_ror:2 row_mask:0xf bank_mask:0xf
	v_mov_b32_dpp v0, v54 row_ror:1 row_mask:0xf bank_mask:0xf
	v_mov_b32_dpp v97, v54 row_ror:2 row_mask:0xf bank_mask:0xf
	v_mov_b32_dpp v109, v55 row_ror:1 row_mask:0xf bank_mask:0xf
	v_mov_b32_dpp v96, v55 row_ror:2 row_mask:0xf bank_mask:0xf
	v_mov_b32_dpp v110, v60 row_ror:1 row_mask:0xf bank_mask:0xf
	v_mov_b32_dpp v99, v60 row_ror:2 row_mask:0xf bank_mask:0xf
	v_mov_b32_dpp v111, v61 row_ror:1 row_mask:0xf bank_mask:0xf
	v_mov_b32_dpp v98, v61 row_ror:2 row_mask:0xf bank_mask:0xf
	v_mov_b32_dpp v112, v82 row_ror:1 row_mask:0xf bank_mask:0xf
	v_mov_b32_dpp v93, v82 row_ror:2 row_mask:0xf bank_mask:0xf
	v_mov_b32_dpp v113, v83 row_ror:1 row_mask:0xf bank_mask:0xf
	v_mov_b32_dpp v92, v83 row_ror:2 row_mask:0xf bank_mask:0xf
	v_mov_b32_dpp v114, v88 row_ror:1 row_mask:0xf bank_mask:0xf
	v_mov_b32_dpp v95, v88 row_ror:2 row_mask:0xf bank_mask:0xf
	v_mov_b32_dpp v115, v89 row_ror:1 row_mask:0xf bank_mask:0xf
	v_mov_b32_dpp v94, v89 row_ror:2 row_mask:0xf bank_mask:0xf
	v_mov_b32_dpp v57, v64 row_ror:1 row_mask:0xf bank_mask:0xf
	v_mov_b32_dpp v101, v64 row_ror:2 row_mask:0xf bank_mask:0xf
	v_mov_b32_dpp v116, v65 row_ror:1 row_mask:0xf bank_mask:0xf
	v_mov_b32_dpp v100, v65 row_ror:2 row_mask:0xf bank_mask:0xf
	v_mov_b32_dpp v117, v68 row_ror:1 row_mask:0xf bank_mask:0xf
	v_mov_b32_dpp v103, v68 row_ror:2 row_mask:0xf bank_mask:0xf
	v_mov_b32_dpp v118, v69 row_ror:1 row_mask:0xf bank_mask:0xf
	v_mov_b32_dpp v102, v69 row_ror:2 row_mask:0xf bank_mask:0xf
	v_cmp_gt_u32_e64 s[42:43], 2, v108
	v_lshl_add_u64 v[10:11], s[96:97], 0, v[22:23]
	v_lshl_add_u64 v[12:13], s[62:63], 0, v[22:23]
	global_load_dwordx4 v[18:21], v[10:11], off
	global_load_dwordx4 v[14:17], v[12:13], off
	v_lshl_add_u64 v[10:11], s[64:65], 0, v[22:23]
	v_lshl_add_u64 v[22:23], s[66:67], 0, v[22:23]
	global_load_dwordx4 v[10:13], v[10:11], off
	s_nop 1
	global_load_dwordx4 v[22:25], v[22:23], off
	s_nop 1
	v_mov_b32_dpp v70, v42 row_ror:1 row_mask:0xf bank_mask:0xf
	v_mov_b32_dpp v76, v42 row_ror:2 row_mask:0xf bank_mask:0xf
	v_mov_b32_dpp v71, v43 row_ror:1 row_mask:0xf bank_mask:0xf
	v_mov_b32_dpp v77, v43 row_ror:2 row_mask:0xf bank_mask:0xf
	v_mov_b32_dpp v74, v72 row_ror:1 row_mask:0xf bank_mask:0xf
	v_mov_b32_dpp v78, v72 row_ror:2 row_mask:0xf bank_mask:0xf
	v_mov_b32_dpp v75, v73 row_ror:1 row_mask:0xf bank_mask:0xf
	v_mov_b32_dpp v79, v73 row_ror:2 row_mask:0xf bank_mask:0xf
	s_and_saveexec_b64 s[0:1], s[42:43]
	s_xor_b64 s[0:1], exec, s[0:1]
	s_or_saveexec_b64 s[0:1], s[0:1]
	v_mov_b64_e32 v[106:107], v[98:99]
	v_mov_b64_e32 v[104:105], v[96:97]
	s_xor_b64 exec, exec, s[0:1]
	s_cbranch_execz .Lcg_skip3
	s_waitcnt vmcnt(4)
	v_pk_fma_f32 v[46:47], v[28:29], v[90:91], v[40:41] op_sel:[0,1,0] op_sel_hi:[1,0,1]
	v_mov_b64_e32 v[106:107], v[94:95]
	v_pk_fma_f32 v[46:47], v[32:33], v[80:81], v[46:47]
	v_mov_b64_e32 v[104:105], v[92:93]
	v_pk_fma_f32 v[46:47], v[84:85], v[36:37], v[46:47]
	v_pk_fma_f32 v[84:85], v[26:27], v[86:87], v[38:39] op_sel:[0,1,0] op_sel_hi:[1,0,1]
	v_pk_fma_f32 v[84:85], v[30:31], v[66:67], v[84:85]
	v_pk_fma_f32 v[44:45], v[44:45], v[34:35], v[84:85]
	v_pk_mul_f32 v[86:87], v[46:47], s[98:99] op_sel_hi:[1,0]
	v_exp_f32_e32 v86, v86
	v_exp_f32_e32 v87, v87
	s_nop 0
	v_pk_add_f32 v[86:87], v[86:87], 1.0 op_sel_hi:[1,0]
	v_rcp_f32_e32 v86, v86
	v_rcp_f32_e32 v87, v87
	s_nop 0
	v_pk_mul_f32 v[46:47], v[46:47], v[86:87]
	s_waitcnt vmcnt(0)
	v_pk_fma_f32 v[86:87], v[18:19], v[76:77], v[22:23]
	v_add_u32_e32 v53, 0x80, v56
	v_pk_fma_f32 v[86:87], v[14:15], v[70:71], v[86:87]
	v_pk_mul_f32 v[84:85], v[44:45], s[98:99] op_sel_hi:[1,0]
	v_exp_f32_e32 v84, v84
	v_exp_f32_e32 v85, v85
	s_nop 0
	v_pk_add_f32 v[84:85], v[84:85], 1.0 op_sel_hi:[1,0]
	v_rcp_f32_e32 v84, v84
	v_rcp_f32_e32 v85, v85
	s_nop 0
	v_pk_mul_f32 v[44:45], v[44:45], v[84:85]
	v_pk_fma_f32 v[42:43], v[42:43], v[10:11], v[86:87]
	v_pk_fma_f32 v[84:85], v[20:21], v[78:79], v[24:25]
	v_pk_mul_f32 v[42:43], v[44:45], v[42:43]
	v_mov_b64_e32 v[44:45], s[36:37]
	v_pk_fma_f32 v[84:85], v[16:17], v[74:75], v[84:85]
	v_mad_i64_i32 v[44:45], s[4:5], v53, s46, v[44:45]
	v_pk_fma_f32 v[72:73], v[72:73], v[12:13], v[84:85]
	v_lshl_add_u64 v[44:45], v[58:59], 1, v[44:45]
	v_mov_b64_e32 v[90:91], v[98:99]
	v_mov_b64_e32 v[86:87], v[96:97]
	v_mov_b64_e32 v[94:95], v[102:103]
	v_mov_b64_e32 v[92:93], v[100:101]
	v_pk_mul_f32 v[46:47], v[46:47], v[72:73]
	v_cvt_pk_bf16_f32 v42, v42, v43
	s_nop 0
	v_cvt_pk_bf16_f32 v43, v46, v47
	v_mov_b32_e32 v236, v228
	v_mov_b32_e32 v237, v229
	v_mov_b32_e32 v238, v42
	v_mov_b32_e32 v239, v43
	global_store_dwordx4 v[44:45], v[236:239], off offset:-8
.LBB0_135:
	s_or_b64 exec, exec, s[0:1]
	v_cmp_eq_u32_e64 s[42:43], 0, v108
	v_add_u32_e32 v96, 0x90, v56
	v_add_u32_e32 v97, 0xa0, v56
	v_add_u32_e32 v98, 0xb0, v56
	v_cndmask_b32_e64 v43, v118, v115, s[42:43]
	v_cndmask_b32_e64 v42, v117, v114, s[42:43]
	s_waitcnt vmcnt(4)
	v_pk_fma_f32 v[44:45], v[28:29], v[94:95], v[40:41] op_sel:[0,1,0] op_sel_hi:[1,0,1]
	v_cndmask_b32_e64 v47, v116, v113, s[42:43]
	v_cndmask_b32_e64 v46, v57, v112, s[42:43]
	v_pk_fma_f32 v[56:57], v[26:27], v[92:93], v[38:39] op_sel:[0,1,0] op_sel_hi:[1,0,1]
	v_pk_fma_f32 v[42:43], v[32:33], v[42:43], v[44:45]
	v_pk_fma_f32 v[46:47], v[30:31], v[46:47], v[56:57]
	v_pk_fma_f32 v[42:43], v[68:69], v[36:37], v[42:43]
	v_pk_fma_f32 v[46:47], v[64:65], v[34:35], v[46:47]
	v_cndmask_b32_e64 v65, v115, v111, s[42:43]
	v_cndmask_b32_e64 v64, v114, v110, s[42:43]
	v_pk_fma_f32 v[68:69], v[28:29], v[106:107], v[40:41] op_sel:[0,1,0] op_sel_hi:[1,0,1]
	v_cndmask_b32_e64 v81, v111, v81, s[42:43]
	v_cndmask_b32_e64 v80, v110, v80, s[42:43]
	v_pk_fma_f32 v[28:29], v[28:29], v[90:91], v[40:41] op_sel:[0,1,0] op_sel_hi:[1,0,1]
	v_pk_fma_f32 v[64:65], v[32:33], v[64:65], v[68:69]
	v_pk_fma_f32 v[28:29], v[32:33], v[80:81], v[28:29]
	v_pk_fma_f32 v[64:65], v[88:89], v[36:37], v[64:65]
	v_pk_fma_f32 v[84:85], v[26:27], v[104:105], v[38:39] op_sel:[0,1,0] op_sel_hi:[1,0,1]
	v_pk_fma_f32 v[28:29], v[60:61], v[36:37], v[28:29]
	v_cndmask_b32_e64 v37, v109, v67, s[42:43]
	v_cndmask_b32_e64 v36, v0, v66, s[42:43]
	v_pk_fma_f32 v[26:27], v[26:27], v[86:87], v[38:39] op_sel:[0,1,0] op_sel_hi:[1,0,1]
	v_cndmask_b32_e64 v72, v112, v0, s[42:43]
	v_pk_fma_f32 v[26:27], v[30:31], v[36:37], v[26:27]
	v_pk_fma_f32 v[26:27], v[54:55], v[34:35], v[26:27]
	v_cndmask_b32_e64 v73, v113, v109, s[42:43]
	v_pk_fma_f32 v[72:73], v[30:31], v[72:73], v[84:85]
	v_pk_fma_f32 v[72:73], v[82:83], v[34:35], v[72:73]
	v_mov_b32_e32 v34, v62
	v_mov_b32_e32 v35, v62
	v_mov_b32_e32 v53, v52
	v_mov_b32_e32 v63, v62
	v_pk_mul_f32 v[4:5], v[4:5], v[34:35]
	v_mov_b32_e32 v34, v52
	v_mov_b32_e32 v35, v52
	v_pk_mul_f32 v[2:3], v[2:3], v[62:63]
	v_pk_mul_f32 v[8:9], v[8:9], v[34:35]
	v_pk_mul_f32 v[6:7], v[6:7], v[52:53]
	s_nop 1
	v_mov_b32_dpp v52, v6 row_ror:2 row_mask:0xf bank_mask:0xf
	s_nop 1
	v_mov_b32_dpp v54, v7 row_ror:2 row_mask:0xf bank_mask:0xf
	s_nop 1
	v_mov_b32_dpp v60, v8 row_ror:2 row_mask:0xf bank_mask:0xf
	s_nop 1
	v_mov_b32_dpp v62, v9 row_ror:2 row_mask:0xf bank_mask:0xf
	v_mov_b32_dpp v0, v6 row_ror:1 row_mask:0xf bank_mask:0xf
	v_mov_b32_dpp v53, v7 row_ror:1 row_mask:0xf bank_mask:0xf
	v_mov_b32_dpp v55, v8 row_ror:1 row_mask:0xf bank_mask:0xf
	v_mov_b32_dpp v61, v9 row_ror:1 row_mask:0xf bank_mask:0xf
	v_cndmask_b32_e32 v34, v76, v52, vcc
	v_cndmask_b32_e32 v35, v77, v54, vcc
	v_cndmask_b32_e32 v36, v78, v60, vcc
	v_cndmask_b32_e32 v37, v79, v62, vcc
	v_cndmask_b32_e64 v38, v0, v70, s[42:43]
	v_cndmask_b32_e64 v39, v53, v71, s[42:43]
	v_cndmask_b32_e64 v40, v55, v74, s[42:43]
	v_cndmask_b32_e64 v41, v61, v75, s[42:43]
	v_pk_mul_f32 v[30:31], v[26:27], s[98:99] op_sel_hi:[1,0]
	v_pk_mul_f32 v[32:33], v[28:29], s[98:99] op_sel_hi:[1,0]
	v_exp_f32_e32 v30, v30
	v_exp_f32_e32 v31, v31
	v_exp_f32_e32 v32, v32
	v_exp_f32_e32 v33, v33
	v_pk_add_f32 v[30:31], v[30:31], 1.0 op_sel_hi:[1,0]
	v_pk_add_f32 v[32:33], v[32:33], 1.0 op_sel_hi:[1,0]
	v_rcp_f32_e32 v30, v30
	v_rcp_f32_e32 v31, v31
	v_rcp_f32_e32 v32, v32
	v_rcp_f32_e32 v33, v33
	v_pk_mul_f32 v[26:27], v[26:27], v[30:31]
	v_pk_mul_f32 v[28:29], v[28:29], v[32:33]
	s_waitcnt vmcnt(1)
	v_pk_fma_f32 v[30:31], v[20:21], v[36:37], v[24:25]
	v_pk_fma_f32 v[32:33], v[18:19], v[34:35], v[22:23]
	v_pk_fma_f32 v[30:31], v[16:17], v[40:41], v[30:31]
	v_pk_fma_f32 v[32:33], v[14:15], v[38:39], v[32:33]
	v_pk_fma_f32 v[8:9], v[8:9], v[12:13], v[30:31]
	v_pk_fma_f32 v[6:7], v[6:7], v[10:11], v[32:33]
	v_pk_mul_f32 v[8:9], v[28:29], v[8:9]
	v_pk_mul_f32 v[6:7], v[26:27], v[6:7]
	v_cvt_pk_bf16_f32 v6, v6, v7
	v_cvt_pk_bf16_f32 v7, v8, v9
	v_mov_b64_e32 v[8:9], s[36:37]
	v_mad_i64_i32 v[26:27], s[0:1], v96, s46, v[8:9]
	v_lshlrev_b64 v[28:29], 1, v[58:59]
	s_nop 1
	v_lshl_add_u64 v[26:27], v[26:27], 0, v[28:29]
	s_nop 1
	v_mov_b32_dpp v39, v2 row_ror:2 row_mask:0xf bank_mask:0xf
	s_nop 1
	v_mov_b32_dpp v41, v3 row_ror:2 row_mask:0xf bank_mask:0xf
	s_nop 1
	v_mov_b32_dpp v59, v4 row_ror:2 row_mask:0xf bank_mask:0xf
	s_nop 1
	v_mov_b32_dpp v66, v5 row_ror:2 row_mask:0xf bank_mask:0xf
	v_mov_b32_e32 v236, v230
	v_mov_b32_e32 v237, v231
	v_mov_b32_e32 v238, v6
	v_mov_b32_e32 v239, v7
	global_store_dwordx4 v[26:27], v[236:239], off offset:-8
	v_mov_b32_dpp v38, v2 row_ror:1 row_mask:0xf bank_mask:0xf
	v_mov_b32_dpp v40, v3 row_ror:1 row_mask:0xf bank_mask:0xf
	v_mov_b32_dpp v58, v4 row_ror:1 row_mask:0xf bank_mask:0xf
	v_mov_b32_dpp v63, v5 row_ror:1 row_mask:0xf bank_mask:0xf
	v_cndmask_b32_e32 v6, v52, v39, vcc
	v_cndmask_b32_e32 v7, v54, v41, vcc
	v_cndmask_b32_e32 v26, v60, v59, vcc
	v_cndmask_b32_e32 v27, v62, v66, vcc
	v_cndmask_b32_e64 v30, v38, v0, s[42:43]
	v_cndmask_b32_e64 v31, v40, v53, s[42:43]
	v_cndmask_b32_e64 v32, v58, v55, s[42:43]
	v_cndmask_b32_e64 v33, v63, v61, s[42:43]
	v_pk_fma_f32 v[26:27], v[20:21], v[26:27], v[24:25]
	v_pk_fma_f32 v[6:7], v[18:19], v[6:7], v[22:23]
	v_pk_fma_f32 v[26:27], v[16:17], v[32:33], v[26:27]
	v_pk_fma_f32 v[6:7], v[14:15], v[30:31], v[6:7]
	v_pk_mul_f32 v[82:83], v[72:73], s[98:99] op_sel_hi:[1,0]
	v_pk_mul_f32 v[68:69], v[64:65], s[98:99] op_sel_hi:[1,0]
	v_exp_f32_e32 v82, v82
	v_exp_f32_e32 v83, v83
	v_exp_f32_e32 v68, v68
	v_exp_f32_e32 v69, v69
	v_pk_add_f32 v[82:83], v[82:83], 1.0 op_sel_hi:[1,0]
	v_pk_add_f32 v[68:69], v[68:69], 1.0 op_sel_hi:[1,0]
	v_rcp_f32_e32 v82, v82
	v_rcp_f32_e32 v83, v83
	v_rcp_f32_e32 v68, v68
	v_rcp_f32_e32 v69, v69
	v_pk_mul_f32 v[34:35], v[72:73], v[82:83]
	v_pk_mul_f32 v[36:37], v[64:65], v[68:69]
	v_pk_fma_f32 v[4:5], v[4:5], v[12:13], v[26:27]
	v_pk_fma_f32 v[2:3], v[2:3], v[10:11], v[6:7]
	v_pk_mul_f32 v[4:5], v[36:37], v[4:5]
	v_pk_mul_f32 v[2:3], v[34:35], v[2:3]
	v_cvt_pk_bf16_f32 v2, v2, v3
	v_cvt_pk_bf16_f32 v3, v4, v5
	v_mad_i64_i32 v[4:5], s[0:1], v97, s46, v[8:9]
	v_lshl_add_u64 v[4:5], v[4:5], 0, v[28:29]
	v_mov_b32_e32 v236, v232
	v_mov_b32_e32 v237, v233
	v_mov_b32_e32 v238, v2
	v_mov_b32_e32 v239, v3
	global_store_dwordx4 v[4:5], v[236:239], off offset:-8
	s_nop 1
	s_nop 1
	v_mov_b32_dpp v2, v50 row_ror:2 row_mask:0xf bank_mask:0xf
	s_nop 1
	v_mov_b32_dpp v3, v51 row_ror:2 row_mask:0xf bank_mask:0xf
	s_nop 1
	v_mov_b32_dpp v4, v48 row_ror:2 row_mask:0xf bank_mask:0xf
	s_nop 1
	v_mov_b32_dpp v5, v49 row_ror:2 row_mask:0xf bank_mask:0xf
	v_mov_b32_dpp v0, v50 row_ror:1 row_mask:0xf bank_mask:0xf
	v_mov_b32_dpp v7, v51 row_ror:1 row_mask:0xf bank_mask:0xf
	v_mov_b32_dpp v26, v48 row_ror:1 row_mask:0xf bank_mask:0xf
	v_mov_b32_dpp v27, v49 row_ror:1 row_mask:0xf bank_mask:0xf
	v_cndmask_b32_e32 v2, v39, v2, vcc
	v_cndmask_b32_e32 v3, v41, v3, vcc
	v_cndmask_b32_e32 v4, v59, v4, vcc
	v_cndmask_b32_e32 v5, v66, v5, vcc
	v_cndmask_b32_e64 v6, v0, v38, s[42:43]
	v_cndmask_b32_e64 v7, v7, v40, s[42:43]
	v_cndmask_b32_e64 v26, v26, v58, s[42:43]
	v_cndmask_b32_e64 v27, v27, v63, s[42:43]
	v_pk_fma_f32 v[2:3], v[18:19], v[2:3], v[22:23]
	v_pk_fma_f32 v[4:5], v[20:21], v[4:5], v[24:25]
	v_pk_fma_f32 v[2:3], v[14:15], v[6:7], v[2:3]
	v_pk_fma_f32 v[4:5], v[16:17], v[26:27], v[4:5]
	v_pk_mul_f32 v[56:57], v[46:47], s[98:99] op_sel_hi:[1,0]
	v_pk_mul_f32 v[44:45], v[42:43], s[98:99] op_sel_hi:[1,0]
	v_exp_f32_e32 v56, v56
	v_exp_f32_e32 v57, v57
	v_exp_f32_e32 v44, v44
	v_exp_f32_e32 v45, v45
	v_pk_add_f32 v[56:57], v[56:57], 1.0 op_sel_hi:[1,0]
	v_pk_add_f32 v[44:45], v[44:45], 1.0 op_sel_hi:[1,0]
	v_rcp_f32_e32 v56, v56
	v_rcp_f32_e32 v57, v57
	v_rcp_f32_e32 v44, v44
	v_rcp_f32_e32 v45, v45
	v_pk_mul_f32 v[30:31], v[46:47], v[56:57]
	v_pk_mul_f32 v[32:33], v[42:43], v[44:45]
	v_pk_fma_f32 v[2:3], v[50:51], v[10:11], v[2:3]
	v_pk_fma_f32 v[4:5], v[48:49], v[12:13], v[4:5]
	v_pk_mul_f32 v[2:3], v[30:31], v[2:3]
	v_pk_mul_f32 v[4:5], v[32:33], v[4:5]
	v_cvt_pk_bf16_f32 v2, v2, v3
	s_nop 0
	v_cvt_pk_bf16_f32 v3, v4, v5
	v_mad_i64_i32 v[4:5], s[0:1], v98, s46, v[8:9]
	v_lshl_add_u64 v[4:5], v[4:5], 0, v[28:29]
	v_mov_b32_e32 v236, v234
	v_mov_b32_e32 v237, v235
	v_mov_b32_e32 v238, v2
	v_mov_b32_e32 v239, v3
	global_store_dwordx4 v[4:5], v[236:239], off offset:-8
	s_andn2_b64 vcc, exec, s[40:41]
	s_mov_b64 s[0:1], -1
	s_cbranch_vccnz .LBB0_102
	s_andn2_b64 vcc, exec, s[30:31]
	s_cbranch_vccnz .LBB0_101
	s_barrier
	s_branch .LBB0_101
